# v6 plus: the 8 A-fragment reads of load phases P1/P5 issued progressively inside the previous MFMA group as their destination registers die (6 hoisted, 2 remain)
# speedup vs baseline: 1.0070x; 1.0070x over previous
; #define PG8_STAGE(bufoff, gbase, voff) do { _Pragma("unroll") for (int _i = 0; _i < 2; ++_i) \
;         __builtin_amdgcn_global_load_lds((const unsigned*)((const char*)(gbase) + (voff)[_i]), (LAS unsigned*)(lds + (bufoff) + ldsw + _i * 8192), 16, 0, 0); } while (0)
; #define PG8_LDA(dst, b, h) do { _Pragma("unroll") for (int m = 0; m < 4; ++m) _Pragma("unroll") for (int k = 0; k < 2; ++k) dst[m][k] = *(const LAS bf16x8*)(lds + PG8_SA(b, h) + aoff + m * 2048 + k * 1024); } while (0)
; #define PG8_LDB(dst, b, h) do { _Pragma("unroll") for (int n = 0; n < 2; ++n) _Pragma("unroll") for (int k = 0; k < 2; ++k) dst[n][k] = *(const LAS bf16x8*)(lds + PG8_SB(b, h) + boff + n * 2048 + k * 1024); } while (0)
; #define PG8_SCHED __builtin_amdgcn_sched_barrier(0)
; template <class Epi, class Sched>
; __device__ __forceinline__ void gemm_phase(LAS unsigned char* lds, const Gemm g, const Sched& S, const Epi& E) {
;     ...
;         const bool has_next = S.next(ui + 1, nxt);
;         const char* nA = has_next ? PG8_APANEL(nxt.pm) : cA; const char* nB = has_next ? (const char*)g.Bt + (size_t)nxt.pn * tstep : cB;
;         for (int t = 0; t < nt; t += 2) {
;             const bool last = (t == nt - 2);
;             const char* a1 = cA + (size_t)(t + 1) * kstep;
;             const char* a2 = last ? nA : cA + (size_t)(t + 2) * kstep; const char* b2 = last ? nB : cB + (size_t)(t + 2) * kstep;
;             const char* a3 = a2 + kstep; const char* b3 = b2 + kstep;
;             PG8_LDB(B0, 0, 0); PG8_SCHED; PG8_LDA(At, 0, 0); PG8_STAGE(PG8_SA(1, 1), a1 + hstep, voffA);
;     ...
; #pragma unroll
;         for (int a = 0; a < 2; ++a)
; #pragma unroll
;             for (int b = 0; b < 2; ++b)
; #pragma unroll
;                 for (int m = 0; m < 4; ++m)
; #pragma unroll
;                     for (int n = 0; n < 2; ++n) acc[a][b][m][n] = (f32x4){0.f, 0.f, 0.f, 0.f};
;         cur = nxt; cA = nA; cB = nB; ++ui;
.LBB0_164:
	s_cmp_lt_i32 s44, 0x100000
	s_cselect_b32 s24, s20, 0xffffff80
	s_cselect_b32 s25, s11, 0
	s_ashr_i32 s45, s44, 31
	s_lshl_b64 s[34:35], s[44:45], 19
	v_cmp_lt_i64_e32 vcc, s[46:47], v[152:153]
	s_add_u32 s46, s25, s34
	s_addc_u32 s47, s24, s35
	s_and_b64 s[34:35], vcc, exec
	s_cselect_b32 s34, s47, s49
	s_cselect_b32 s45, s46, s48
	s_ashr_i32 s43, s42, 31
	s_lshl_b64 s[60:61], s[42:43], 19
	s_add_u32 s76, s16, s60
	s_addc_u32 s77, s92, s61
	s_and_b64 s[60:61], vcc, exec
	s_cselect_b32 s43, s77, s39
	s_cselect_b32 s79, s76, s38
	s_add_u32 vcc_lo, s38, 0x100
	s_addc_u32 s35, s39, 0
	s_add_u32 s38, s48, 0x40080
	v_mov_b32_e32 v2, 0
	s_addc_u32 s39, s49, 0
	s_mov_b32 s50, -2
	v_mov_b32_e32 v3, v2
	v_mov_b32_e32 v4, v2
	v_mov_b32_e32 v5, v2
	v_mov_b32_e32 v6, v2
	v_mov_b32_e32 v7, v2
	v_mov_b32_e32 v8, v2
	v_mov_b32_e32 v9, v2
	v_mov_b32_e32 v18, v2
	v_mov_b32_e32 v19, v2
	v_mov_b32_e32 v20, v2
	v_mov_b32_e32 v21, v2
	v_mov_b32_e32 v22, v2
	v_mov_b32_e32 v23, v2
	v_mov_b32_e32 v24, v2
	v_mov_b32_e32 v25, v2
	v_mov_b32_e32 v34, v2
	v_mov_b32_e32 v35, v2
	v_mov_b32_e32 v36, v2
	v_mov_b32_e32 v37, v2
	v_mov_b32_e32 v38, v2
	v_mov_b32_e32 v39, v2
	v_mov_b32_e32 v40, v2
	v_mov_b32_e32 v41, v2
	v_mov_b32_e32 v50, v2
	v_mov_b32_e32 v51, v2
	v_mov_b32_e32 v52, v2
	v_mov_b32_e32 v53, v2
	v_mov_b32_e32 v54, v2
	v_mov_b32_e32 v55, v2
	v_mov_b32_e32 v56, v2
	v_mov_b32_e32 v57, v2
	v_mov_b32_e32 v10, v2
	v_mov_b32_e32 v11, v2
	v_mov_b32_e32 v12, v2
	v_mov_b32_e32 v13, v2
	v_mov_b32_e32 v14, v2
	v_mov_b32_e32 v15, v2
	v_mov_b32_e32 v16, v2
	v_mov_b32_e32 v17, v2
	v_mov_b32_e32 v26, v2
	v_mov_b32_e32 v27, v2
	v_mov_b32_e32 v28, v2
	v_mov_b32_e32 v29, v2
	v_mov_b32_e32 v30, v2
	v_mov_b32_e32 v31, v2
	v_mov_b32_e32 v32, v2
	v_mov_b32_e32 v33, v2
	v_mov_b32_e32 v42, v2
	v_mov_b32_e32 v43, v2
	v_mov_b32_e32 v44, v2
	v_mov_b32_e32 v45, v2
	v_mov_b32_e32 v46, v2
	v_mov_b32_e32 v47, v2
	v_mov_b32_e32 v48, v2
	v_mov_b32_e32 v49, v2
	v_mov_b32_e32 v58, v2
	v_mov_b32_e32 v59, v2
	v_mov_b32_e32 v60, v2
	v_mov_b32_e32 v61, v2
	v_mov_b32_e32 v62, v2
	v_mov_b32_e32 v63, v2
	v_mov_b32_e32 v64, v2
	v_mov_b32_e32 v65, v2
	v_mov_b32_e32 v66, v2
	v_mov_b32_e32 v67, v2
	v_mov_b32_e32 v68, v2
	v_mov_b32_e32 v69, v2
	v_mov_b32_e32 v70, v2
	v_mov_b32_e32 v71, v2
	v_mov_b32_e32 v72, v2
	v_mov_b32_e32 v73, v2
	v_mov_b32_e32 v82, v2
	v_mov_b32_e32 v83, v2
	v_mov_b32_e32 v84, v2
	v_mov_b32_e32 v85, v2
	v_mov_b32_e32 v86, v2
	v_mov_b32_e32 v87, v2
	v_mov_b32_e32 v88, v2
	v_mov_b32_e32 v89, v2
	v_mov_b32_e32 v98, v2
	v_mov_b32_e32 v99, v2
	v_mov_b32_e32 v100, v2
	v_mov_b32_e32 v101, v2
	v_mov_b32_e32 v102, v2
	v_mov_b32_e32 v103, v2
	v_mov_b32_e32 v104, v2
	v_mov_b32_e32 v105, v2
	v_mov_b32_e32 v114, v2
	v_mov_b32_e32 v115, v2
	v_mov_b32_e32 v116, v2
	v_mov_b32_e32 v117, v2
	v_mov_b32_e32 v118, v2
	v_mov_b32_e32 v119, v2
	v_mov_b32_e32 v120, v2
	v_mov_b32_e32 v121, v2
	v_mov_b32_e32 v74, v2
	v_mov_b32_e32 v75, v2
	v_mov_b32_e32 v76, v2
	v_mov_b32_e32 v77, v2
	v_mov_b32_e32 v78, v2
	v_mov_b32_e32 v79, v2
	v_mov_b32_e32 v80, v2
	v_mov_b32_e32 v81, v2
	v_mov_b32_e32 v90, v2
	v_mov_b32_e32 v91, v2
	v_mov_b32_e32 v92, v2
	v_mov_b32_e32 v93, v2
	v_mov_b32_e32 v94, v2
	v_mov_b32_e32 v95, v2
	v_mov_b32_e32 v96, v2
	v_mov_b32_e32 v97, v2
	v_mov_b32_e32 v106, v2
	v_mov_b32_e32 v107, v2
	v_mov_b32_e32 v108, v2
	v_mov_b32_e32 v109, v2
	v_mov_b32_e32 v110, v2
	v_mov_b32_e32 v111, v2
	v_mov_b32_e32 v112, v2
	v_mov_b32_e32 v113, v2
	v_mov_b32_e32 v122, v2
	v_mov_b32_e32 v123, v2
	v_mov_b32_e32 v124, v2
	v_mov_b32_e32 v125, v2
	v_mov_b32_e32 v126, v2
	v_mov_b32_e32 v127, v2
	v_mov_b32_e32 v128, v2
	v_mov_b32_e32 v129, v2
	v_add_u32_e32 v249, 0x10000, v167
	ds_read_b128 v[142:145], v249
	ds_read_b128 v[162:165], v249 offset:1024
	ds_read_b128 v[182:185], v249 offset:2048
	ds_read_b128 v[186:189], v249 offset:3072
	ds_read_b128 v[190:193], v169
	ds_read_b128 v[194:197], v169 offset:1024
	ds_read_b128 v[198:201], v169 offset:2048
	ds_read_b128 v[202:205], v169 offset:3072
	ds_read_b128 v[206:209], v169 offset:4096
	ds_read_b128 v[210:213], v169 offset:5120
.LBB0_165:
	s_add_u32 s24, s38, 0xfffc0080
	s_addc_u32 s25, s39, -1
	s_add_i32 vcc_hi, 0, 0x10000
	v_add_u32_e32 v166, vcc_hi, v167
	s_cmp_eq_u32 s50, 12
	s_cselect_b32 s61, s34, s25
	s_cselect_b32 s60, s45, s24
	s_cselect_b32 s49, s43, s35
	s_cselect_b32 s48, s79, vcc_lo
	v_lshl_add_u64 v[222:223], s[38:39], 0, v[140:141]
	s_add_i32 m0, s93, 0xc000
	ds_read_b128 v[214:217], v169 offset:6144
	ds_read_b128 v[218:221], v169 offset:7168
	global_load_lds_dwordx4 v[222:223], off
	v_lshl_add_u64 v[250:251], s[38:39], 0, v[138:139]
	s_add_i32 m0, s93, 0xe000
	s_nop 0
	global_load_lds_dwordx4 v[250:251], off
	s_waitcnt lgkmcnt(8)
	s_barrier
	s_waitcnt lgkmcnt(0)
	s_setprio 1
	s_waitcnt lgkmcnt(0)
	v_mfma_f32_16x16x32_bf16 v[126:129], v[142:145], v[190:193], v[126:129]
	v_mfma_f32_16x16x32_bf16 v[126:129], v[162:165], v[194:197], v[126:129]
	v_mfma_f32_16x16x32_bf16 v[122:125], v[182:185], v[190:193], v[122:125]
	v_mfma_f32_16x16x32_bf16 v[122:125], v[186:189], v[194:197], v[122:125]
	v_mfma_f32_16x16x32_bf16 v[110:113], v[142:145], v[198:201], v[110:113]
	v_mfma_f32_16x16x32_bf16 v[110:113], v[162:165], v[202:205], v[110:113]
	v_mfma_f32_16x16x32_bf16 v[106:109], v[182:185], v[198:201], v[106:109]
	v_mfma_f32_16x16x32_bf16 v[106:109], v[186:189], v[202:205], v[106:109]
	v_mfma_f32_16x16x32_bf16 v[94:97], v[142:145], v[206:209], v[94:97]
	v_mfma_f32_16x16x32_bf16 v[94:97], v[162:165], v[210:213], v[94:97]
	v_mfma_f32_16x16x32_bf16 v[90:93], v[182:185], v[206:209], v[90:93]
	v_mfma_f32_16x16x32_bf16 v[90:93], v[186:189], v[210:213], v[90:93]
	v_mfma_f32_16x16x32_bf16 v[78:81], v[142:145], v[214:217], v[78:81]
	v_mfma_f32_16x16x32_bf16 v[78:81], v[162:165], v[218:221], v[78:81]
	v_mfma_f32_16x16x32_bf16 v[74:77], v[182:185], v[214:217], v[74:77]
	s_barrier
; #define PG8_STAGE(bufoff, gbase, voff) do { _Pragma("unroll") for (int _i = 0; _i < 2; ++_i) \
;         __builtin_amdgcn_global_load_lds((const unsigned*)((const char*)(gbase) + (voff)[_i]), (LAS unsigned*)(lds + (bufoff) + ldsw + _i * 8192), 16, 0, 0); } while (0)
; #define PG8_LDA(dst, b, h) do { _Pragma("unroll") for (int m = 0; m < 4; ++m) _Pragma("unroll") for (int k = 0; k < 2; ++k) dst[m][k] = *(const LAS bf16x8*)(lds + PG8_SA(b, h) + aoff + m * 2048 + k * 1024); } while (0)
; #define PG8_LDB(dst, b, h) do { _Pragma("unroll") for (int n = 0; n < 2; ++n) _Pragma("unroll") for (int k = 0; k < 2; ++k) dst[n][k] = *(const LAS bf16x8*)(lds + PG8_SB(b, h) + boff + n * 2048 + k * 1024); } while (0)
; #define PG8_MMA(ai, bj, At, Bt) do { __builtin_amdgcn_s_setprio(1); _Pragma("unroll") for (int m = 0; m < 4; ++m) _Pragma("unroll") for (int n = 0; n < 2; ++n) _Pragma("unroll") for (int k = 0; k < 2; ++k) \
;         acc[ai][bj][m][n] = __builtin_amdgcn_mfma_f32_16x16x32_bf16(Bt[n][k], At[m][k], acc[ai][bj][m][n], 0, 0, 0); __builtin_amdgcn_s_setprio(0); } while (0)
; #define PG8_WAIT_V(n) asm volatile("s_waitcnt vmcnt(" #n ")" ::: "memory")
; #define PG8_WAIT_L(n) asm volatile("s_waitcnt lgkmcnt(" #n ")" ::: "memory")
; #define PG8_BAR __builtin_amdgcn_s_barrier()
; #define PG8_SCHED __builtin_amdgcn_sched_barrier(0)
; template <class Epi, class Sched>
; __device__ __forceinline__ void gemm_phase(LAS unsigned char* lds, const Gemm g, const Sched& S, const Epi& E) {
;     ...
;             PG8_WAIT_L(8); PG8_BAR; PG8_WAIT_L(0); PG8_MMA(0, 0, At, B0); PG8_BAR; PG8_SCHED;
;             PG8_LDB(B1, 0, 1); PG8_STAGE(PG8_SB(0, 0), b2, voffB);
;             PG8_BAR; PG8_WAIT_L(0); PG8_MMA(0, 1, At, B1); PG8_BAR;
;             PG8_LDA(At, 0, 1); PG8_STAGE(PG8_SA(0, 0), a2, voffA);
;             PG8_BAR; PG8_WAIT_L(0); PG8_MMA(1, 0, At, B0); PG8_BAR; PG8_SCHED;
;             PG8_STAGE(PG8_SB(0, 1), b2 + hstep, voffB);
;             PG8_WAIT_V(6); PG8_BAR; PG8_MMA(1, 1, At, B1); PG8_BAR;
;             PG8_LDB(B0, 1, 0); PG8_SCHED; PG8_LDA(At, 1, 0); PG8_STAGE(PG8_SA(0, 1), a2 + hstep, voffA);
;             PG8_WAIT_L(8); PG8_BAR; PG8_WAIT_L(0); PG8_MMA(0, 0, At, B0); PG8_BAR; PG8_SCHED;
	v_mfma_f32_16x16x32_bf16 v[74:77], v[186:189], v[218:221], v[74:77]
	s_setprio 0
	s_add_i32 s51, 0, 0x14000
	s_add_i32 s24, vcc_hi, s86
	v_add_u32_e32 v166, s51, v167
	v_lshl_add_u64 v[238:239], s[48:49], 0, v[134:135]
	s_mov_b32 m0, s24
	ds_read_b128 v[222:225], v166
	ds_read_b128 v[226:229], v166 offset:1024
	ds_read_b128 v[230:233], v166 offset:2048
	ds_read_b128 v[234:237], v166 offset:3072
	global_load_lds_dwordx4 v[238:239], off
	v_lshl_add_u64 v[240:241], s[48:49], 0, v[130:131]
	s_add_i32 m0, s24, 0x2000
	s_nop 0
	global_load_lds_dwordx4 v[240:241], off
	s_barrier
	s_waitcnt lgkmcnt(0)
	s_setprio 1
	s_waitcnt lgkmcnt(0)
	v_mfma_f32_16x16x32_bf16 v[118:121], v[222:225], v[190:193], v[118:121]
	v_mfma_f32_16x16x32_bf16 v[118:121], v[226:229], v[194:197], v[118:121]
	v_mfma_f32_16x16x32_bf16 v[114:117], v[230:233], v[190:193], v[114:117]
	v_mfma_f32_16x16x32_bf16 v[114:117], v[234:237], v[194:197], v[114:117]
	v_mfma_f32_16x16x32_bf16 v[102:105], v[222:225], v[198:201], v[102:105]
	v_mfma_f32_16x16x32_bf16 v[102:105], v[226:229], v[202:205], v[102:105]
	v_mfma_f32_16x16x32_bf16 v[98:101], v[230:233], v[198:201], v[98:101]
	v_mfma_f32_16x16x32_bf16 v[98:101], v[234:237], v[202:205], v[98:101]
	v_mfma_f32_16x16x32_bf16 v[86:89], v[222:225], v[206:209], v[86:89]
	v_mfma_f32_16x16x32_bf16 v[86:89], v[226:229], v[210:213], v[86:89]
	v_mfma_f32_16x16x32_bf16 v[82:85], v[230:233], v[206:209], v[82:85]
	v_mfma_f32_16x16x32_bf16 v[82:85], v[234:237], v[210:213], v[82:85]
	v_mfma_f32_16x16x32_bf16 v[70:73], v[222:225], v[214:217], v[70:73]
	v_mfma_f32_16x16x32_bf16 v[70:73], v[226:229], v[218:221], v[70:73]
	v_mfma_f32_16x16x32_bf16 v[66:69], v[230:233], v[214:217], v[66:69]
	s_barrier
	v_mfma_f32_16x16x32_bf16 v[66:69], v[234:237], v[218:221], v[66:69]
	s_setprio 0
	s_mov_b32 m0, s93
	v_lshl_add_u64 v[242:243], s[60:61], 0, v[136:137]
	ds_read_b128 v[190:193], v169 offset:16384
	ds_read_b128 v[194:197], v169 offset:17408
	ds_read_b128 v[198:201], v169 offset:18432
	ds_read_b128 v[202:205], v169 offset:19456
	ds_read_b128 v[206:209], v169 offset:20480
	ds_read_b128 v[210:213], v169 offset:21504
	ds_read_b128 v[214:217], v169 offset:22528
	ds_read_b128 v[218:221], v169 offset:23552
	global_load_lds_dwordx4 v[242:243], off
	v_lshl_add_u64 v[244:245], s[60:61], 0, v[132:133]
	s_mov_b32 m0, s98
	s_nop 0
	global_load_lds_dwordx4 v[244:245], off
	s_waitcnt vmcnt(8)
	s_barrier
	s_waitcnt lgkmcnt(0)
	s_setprio 1
	s_waitcnt lgkmcnt(0)
	v_mfma_f32_16x16x32_bf16 v[62:65], v[142:145], v[190:193], v[62:65]
	v_mfma_f32_16x16x32_bf16 v[62:65], v[162:165], v[194:197], v[62:65]
	v_mfma_f32_16x16x32_bf16 v[58:61], v[182:185], v[190:193], v[58:61]
	v_mfma_f32_16x16x32_bf16 v[58:61], v[186:189], v[194:197], v[58:61]
	v_mfma_f32_16x16x32_bf16 v[46:49], v[142:145], v[198:201], v[46:49]
	v_mfma_f32_16x16x32_bf16 v[46:49], v[162:165], v[202:205], v[46:49]
	v_mfma_f32_16x16x32_bf16 v[42:45], v[182:185], v[198:201], v[42:45]
	v_mfma_f32_16x16x32_bf16 v[42:45], v[186:189], v[202:205], v[42:45]
	v_mfma_f32_16x16x32_bf16 v[30:33], v[142:145], v[206:209], v[30:33]
	v_mfma_f32_16x16x32_bf16 v[30:33], v[162:165], v[210:213], v[30:33]
	v_mfma_f32_16x16x32_bf16 v[26:29], v[182:185], v[206:209], v[26:29]
	v_mfma_f32_16x16x32_bf16 v[26:29], v[186:189], v[210:213], v[26:29]
	v_mfma_f32_16x16x32_bf16 v[14:17], v[142:145], v[214:217], v[14:17]
	v_mfma_f32_16x16x32_bf16 v[14:17], v[162:165], v[218:221], v[14:17]
	v_mfma_f32_16x16x32_bf16 v[10:13], v[182:185], v[214:217], v[10:13]
	s_barrier
	v_mfma_f32_16x16x32_bf16 v[10:13], v[186:189], v[218:221], v[10:13]
	s_setprio 0
	s_add_u32 s24, s48, 0x40000
	s_addc_u32 s25, s49, 0
	s_add_i32 s51, s51, s86
	v_lshl_add_u64 v[142:143], s[24:25], 0, v[134:135]
	s_mov_b32 m0, s51
	s_nop 0
	global_load_lds_dwordx4 v[142:143], off
	v_lshl_add_u64 v[250:251], s[24:25], 0, v[130:131]
	s_add_i32 m0, s51, 0x2000
	s_nop 0
	global_load_lds_dwordx4 v[250:251], off
	s_waitcnt vmcnt(6)
	s_barrier
	s_setprio 1
	v_add_u32_e32 v249, 0x18000, v167
	v_mfma_f32_16x16x32_bf16 v[54:57], v[222:225], v[190:193], v[54:57]
	ds_read_b128 v[142:145], v249
	ds_read_b128 v[162:165], v249 offset:1024
	v_mfma_f32_16x16x32_bf16 v[54:57], v[226:229], v[194:197], v[54:57]
	ds_read_b128 v[182:185], v249 offset:2048
	ds_read_b128 v[186:189], v249 offset:3072
	v_mfma_f32_16x16x32_bf16 v[50:53], v[230:233], v[190:193], v[50:53]
	ds_read_b128 v[190:193], v169 offset:32768
	v_mfma_f32_16x16x32_bf16 v[50:53], v[234:237], v[194:197], v[50:53]
	ds_read_b128 v[194:197], v169 offset:33792
	v_mfma_f32_16x16x32_bf16 v[38:41], v[222:225], v[198:201], v[38:41]
	v_mfma_f32_16x16x32_bf16 v[38:41], v[226:229], v[202:205], v[38:41]
	v_mfma_f32_16x16x32_bf16 v[34:37], v[230:233], v[198:201], v[34:37]
	ds_read_b128 v[198:201], v169 offset:34816
	v_mfma_f32_16x16x32_bf16 v[34:37], v[234:237], v[202:205], v[34:37]
	ds_read_b128 v[202:205], v169 offset:35840
	v_mfma_f32_16x16x32_bf16 v[22:25], v[222:225], v[206:209], v[22:25]
	v_mfma_f32_16x16x32_bf16 v[22:25], v[226:229], v[210:213], v[22:25]
	v_mfma_f32_16x16x32_bf16 v[18:21], v[230:233], v[206:209], v[18:21]
	ds_read_b128 v[206:209], v169 offset:36864
	v_mfma_f32_16x16x32_bf16 v[18:21], v[234:237], v[210:213], v[18:21]
	ds_read_b128 v[210:213], v169 offset:37888
	v_mfma_f32_16x16x32_bf16 v[6:9], v[222:225], v[214:217], v[6:9]
	v_mfma_f32_16x16x32_bf16 v[6:9], v[226:229], v[218:221], v[6:9]
	v_mfma_f32_16x16x32_bf16 v[2:5], v[230:233], v[214:217], v[2:5]
	s_barrier
; #define PG8_STAGE(bufoff, gbase, voff) do { _Pragma("unroll") for (int _i = 0; _i < 2; ++_i) \
;         __builtin_amdgcn_global_load_lds((const unsigned*)((const char*)(gbase) + (voff)[_i]), (LAS unsigned*)(lds + (bufoff) + ldsw + _i * 8192), 16, 0, 0); } while (0)
; #define PG8_LDA(dst, b, h) do { _Pragma("unroll") for (int m = 0; m < 4; ++m) _Pragma("unroll") for (int k = 0; k < 2; ++k) dst[m][k] = *(const LAS bf16x8*)(lds + PG8_SA(b, h) + aoff + m * 2048 + k * 1024); } while (0)
; #define PG8_LDB(dst, b, h) do { _Pragma("unroll") for (int n = 0; n < 2; ++n) _Pragma("unroll") for (int k = 0; k < 2; ++k) dst[n][k] = *(const LAS bf16x8*)(lds + PG8_SB(b, h) + boff + n * 2048 + k * 1024); } while (0)
; #define PG8_MMA(ai, bj, At, Bt) do { __builtin_amdgcn_s_setprio(1); _Pragma("unroll") for (int m = 0; m < 4; ++m) _Pragma("unroll") for (int n = 0; n < 2; ++n) _Pragma("unroll") for (int k = 0; k < 2; ++k) \
;         acc[ai][bj][m][n] = __builtin_amdgcn_mfma_f32_16x16x32_bf16(Bt[n][k], At[m][k], acc[ai][bj][m][n], 0, 0, 0); __builtin_amdgcn_s_setprio(0); } while (0)
; #define PG8_WAIT_L(n) asm volatile("s_waitcnt lgkmcnt(" #n ")" ::: "memory")
; #define PG8_BAR __builtin_amdgcn_s_barrier()
; #define PG8_SCHED __builtin_amdgcn_sched_barrier(0)
; template <class Epi, class Sched>
; __device__ __forceinline__ void gemm_phase(LAS unsigned char* lds, const Gemm g, const Sched& S, const Epi& E) {
;     ...
;             PG8_LDB(B0, 1, 0); PG8_SCHED; PG8_LDA(At, 1, 0); PG8_STAGE(PG8_SA(0, 1), a2 + hstep, voffA);
;             PG8_WAIT_L(8); PG8_BAR; PG8_WAIT_L(0); PG8_MMA(0, 0, At, B0); PG8_BAR; PG8_SCHED;
;             PG8_LDB(B1, 1, 1); PG8_STAGE(PG8_SB(1, 0), b3, voffB);
;             PG8_BAR; PG8_WAIT_L(0); PG8_MMA(0, 1, At, B1); PG8_BAR;
	v_mfma_f32_16x16x32_bf16 v[2:5], v[234:237], v[218:221], v[2:5]
	s_setprio 0
	s_add_i32 s51, 0, 0x18000
	v_add_u32_e32 v166, s51, v167
	s_add_u32 s24, s60, 0x40000
	s_addc_u32 s25, s61, 0
	s_mov_b32 m0, s99
	v_lshl_add_u64 v[222:223], s[24:25], 0, v[136:137]
	ds_read_b128 v[214:217], v169 offset:38912
	ds_read_b128 v[218:221], v169 offset:39936
	global_load_lds_dwordx4 v[222:223], off
	v_lshl_add_u64 v[250:251], s[24:25], 0, v[132:133]
	s_mov_b32 m0, s94
	s_nop 0
	global_load_lds_dwordx4 v[250:251], off
	s_waitcnt lgkmcnt(8)
	s_barrier
	s_waitcnt lgkmcnt(0)
	s_setprio 1
	s_waitcnt lgkmcnt(0)
	v_mfma_f32_16x16x32_bf16 v[126:129], v[142:145], v[190:193], v[126:129]
	v_mfma_f32_16x16x32_bf16 v[126:129], v[162:165], v[194:197], v[126:129]
	v_mfma_f32_16x16x32_bf16 v[122:125], v[182:185], v[190:193], v[122:125]
	v_mfma_f32_16x16x32_bf16 v[122:125], v[186:189], v[194:197], v[122:125]
	v_mfma_f32_16x16x32_bf16 v[110:113], v[142:145], v[198:201], v[110:113]
	v_mfma_f32_16x16x32_bf16 v[110:113], v[162:165], v[202:205], v[110:113]
	v_mfma_f32_16x16x32_bf16 v[106:109], v[182:185], v[198:201], v[106:109]
	v_mfma_f32_16x16x32_bf16 v[106:109], v[186:189], v[202:205], v[106:109]
	v_mfma_f32_16x16x32_bf16 v[94:97], v[142:145], v[206:209], v[94:97]
	v_mfma_f32_16x16x32_bf16 v[94:97], v[162:165], v[210:213], v[94:97]
	v_mfma_f32_16x16x32_bf16 v[90:93], v[182:185], v[206:209], v[90:93]
	v_mfma_f32_16x16x32_bf16 v[90:93], v[186:189], v[210:213], v[90:93]
	v_mfma_f32_16x16x32_bf16 v[78:81], v[142:145], v[214:217], v[78:81]
	v_mfma_f32_16x16x32_bf16 v[78:81], v[162:165], v[218:221], v[78:81]
	v_mfma_f32_16x16x32_bf16 v[74:77], v[182:185], v[214:217], v[74:77]
	s_barrier
	v_mfma_f32_16x16x32_bf16 v[74:77], v[186:189], v[218:221], v[74:77]
	s_setprio 0
	s_add_i32 s60, 0, 0x1c000
	s_add_i32 s24, s51, s86
	v_add_u32_e32 v166, s60, v167
	v_lshl_add_u64 v[238:239], v[238:239], 0, s[12:13]
	s_mov_b32 m0, s24
	ds_read_b128 v[222:225], v166
	ds_read_b128 v[226:229], v166 offset:1024
	ds_read_b128 v[230:233], v166 offset:2048
	ds_read_b128 v[234:237], v166 offset:3072
	global_load_lds_dwordx4 v[238:239], off
	v_lshl_add_u64 v[250:251], v[240:241], 0, s[12:13]
	s_add_i32 m0, s24, 0x2000
	s_nop 0
	global_load_lds_dwordx4 v[250:251], off
	s_barrier
	s_waitcnt lgkmcnt(0)
	s_setprio 1
	s_waitcnt lgkmcnt(0)
	v_mfma_f32_16x16x32_bf16 v[118:121], v[222:225], v[190:193], v[118:121]
	v_mfma_f32_16x16x32_bf16 v[118:121], v[226:229], v[194:197], v[118:121]
	v_mfma_f32_16x16x32_bf16 v[114:117], v[230:233], v[190:193], v[114:117]
	v_mfma_f32_16x16x32_bf16 v[114:117], v[234:237], v[194:197], v[114:117]
	v_mfma_f32_16x16x32_bf16 v[102:105], v[222:225], v[198:201], v[102:105]
	v_mfma_f32_16x16x32_bf16 v[102:105], v[226:229], v[202:205], v[102:105]
	v_mfma_f32_16x16x32_bf16 v[98:101], v[230:233], v[198:201], v[98:101]
	v_mfma_f32_16x16x32_bf16 v[98:101], v[234:237], v[202:205], v[98:101]
	v_mfma_f32_16x16x32_bf16 v[86:89], v[222:225], v[206:209], v[86:89]
	v_mfma_f32_16x16x32_bf16 v[86:89], v[226:229], v[210:213], v[86:89]
	v_mfma_f32_16x16x32_bf16 v[82:85], v[230:233], v[206:209], v[82:85]
	v_mfma_f32_16x16x32_bf16 v[82:85], v[234:237], v[210:213], v[82:85]
	v_mfma_f32_16x16x32_bf16 v[70:73], v[222:225], v[214:217], v[70:73]
	v_mfma_f32_16x16x32_bf16 v[70:73], v[226:229], v[218:221], v[70:73]
	v_mfma_f32_16x16x32_bf16 v[66:69], v[230:233], v[214:217], v[66:69]
	s_barrier
; #define PG8_STAGE(bufoff, gbase, voff) do { _Pragma("unroll") for (int _i = 0; _i < 2; ++_i) \
;         __builtin_amdgcn_global_load_lds((const unsigned*)((const char*)(gbase) + (voff)[_i]), (LAS unsigned*)(lds + (bufoff) + ldsw + _i * 8192), 16, 0, 0); } while (0)
; #define PG8_LDA(dst, b, h) do { _Pragma("unroll") for (int m = 0; m < 4; ++m) _Pragma("unroll") for (int k = 0; k < 2; ++k) dst[m][k] = *(const LAS bf16x8*)(lds + PG8_SA(b, h) + aoff + m * 2048 + k * 1024); } while (0)
; #define PG8_LDB(dst, b, h) do { _Pragma("unroll") for (int n = 0; n < 2; ++n) _Pragma("unroll") for (int k = 0; k < 2; ++k) dst[n][k] = *(const LAS bf16x8*)(lds + PG8_SB(b, h) + boff + n * 2048 + k * 1024); } while (0)
; #define PG8_MMA(ai, bj, At, Bt) do { __builtin_amdgcn_s_setprio(1); _Pragma("unroll") for (int m = 0; m < 4; ++m) _Pragma("unroll") for (int n = 0; n < 2; ++n) _Pragma("unroll") for (int k = 0; k < 2; ++k) \
;         acc[ai][bj][m][n] = __builtin_amdgcn_mfma_f32_16x16x32_bf16(Bt[n][k], At[m][k], acc[ai][bj][m][n], 0, 0, 0); __builtin_amdgcn_s_setprio(0); } while (0)
; #define PG8_WAIT_V(n) asm volatile("s_waitcnt vmcnt(" #n ")" ::: "memory")
; #define PG8_WAIT_L(n) asm volatile("s_waitcnt lgkmcnt(" #n ")" ::: "memory")
; #define PG8_BAR __builtin_amdgcn_s_barrier()
; #define PG8_SCHED __builtin_amdgcn_sched_barrier(0)
; template <class Epi, class Sched>
; __device__ __forceinline__ void gemm_phase(LAS unsigned char* lds, const Gemm g, const Sched& S, const Epi& E) {
;     ...
;             PG8_LDB(B0, 0, 0); PG8_SCHED; PG8_LDA(At, 0, 0); PG8_STAGE(PG8_SA(1, 1), a1 + hstep, voffA);
;     ...
;             PG8_LDA(At, 1, 1); PG8_STAGE(PG8_SA(1, 0), a3, voffA);
;             PG8_BAR; PG8_WAIT_L(0); PG8_MMA(1, 0, At, B0); PG8_BAR; PG8_SCHED;
;             PG8_STAGE(PG8_SB(1, 1), b3 + hstep, voffB);
;             PG8_WAIT_V(6); PG8_BAR; PG8_MMA(1, 1, At, B1); PG8_BAR;
;         }
;         if (wr == 0) PG8_BAR;
	v_mfma_f32_16x16x32_bf16 v[66:69], v[234:237], v[218:221], v[66:69]
	s_setprio 0
	s_mov_b32 m0, s95
	v_lshl_add_u64 v[238:239], v[242:243], 0, s[12:13]
	ds_read_b128 v[190:193], v169 offset:49152
	ds_read_b128 v[194:197], v169 offset:50176
	ds_read_b128 v[198:201], v169 offset:51200
	ds_read_b128 v[202:205], v169 offset:52224
	ds_read_b128 v[206:209], v169 offset:53248
	ds_read_b128 v[210:213], v169 offset:54272
	ds_read_b128 v[214:217], v169 offset:55296
	ds_read_b128 v[218:221], v169 offset:56320
	global_load_lds_dwordx4 v[238:239], off
	v_lshl_add_u64 v[250:251], v[244:245], 0, s[12:13]
	s_mov_b32 m0, s96
	s_nop 0
	global_load_lds_dwordx4 v[250:251], off
	s_waitcnt vmcnt(8)
	s_barrier
	s_waitcnt lgkmcnt(0)
	s_setprio 1
	s_waitcnt lgkmcnt(0)
	v_mfma_f32_16x16x32_bf16 v[62:65], v[142:145], v[190:193], v[62:65]
	v_mfma_f32_16x16x32_bf16 v[62:65], v[162:165], v[194:197], v[62:65]
	v_mfma_f32_16x16x32_bf16 v[58:61], v[182:185], v[190:193], v[58:61]
	v_mfma_f32_16x16x32_bf16 v[58:61], v[186:189], v[194:197], v[58:61]
	v_mfma_f32_16x16x32_bf16 v[46:49], v[142:145], v[198:201], v[46:49]
	v_mfma_f32_16x16x32_bf16 v[46:49], v[162:165], v[202:205], v[46:49]
	v_mfma_f32_16x16x32_bf16 v[42:45], v[182:185], v[198:201], v[42:45]
	v_mfma_f32_16x16x32_bf16 v[42:45], v[186:189], v[202:205], v[42:45]
	v_mfma_f32_16x16x32_bf16 v[30:33], v[142:145], v[206:209], v[30:33]
	v_mfma_f32_16x16x32_bf16 v[30:33], v[162:165], v[210:213], v[30:33]
	v_mfma_f32_16x16x32_bf16 v[26:29], v[182:185], v[206:209], v[26:29]
	v_mfma_f32_16x16x32_bf16 v[26:29], v[186:189], v[210:213], v[26:29]
	v_mfma_f32_16x16x32_bf16 v[14:17], v[142:145], v[214:217], v[14:17]
	v_mfma_f32_16x16x32_bf16 v[14:17], v[162:165], v[218:221], v[14:17]
	v_mfma_f32_16x16x32_bf16 v[10:13], v[182:185], v[214:217], v[10:13]
	s_barrier
	v_mfma_f32_16x16x32_bf16 v[10:13], v[186:189], v[218:221], v[10:13]
	s_setprio 0
	s_add_u32 s24, s48, 0x40080
	s_addc_u32 s25, s49, 0
	s_add_i32 s48, s60, s86
	v_lshl_add_u64 v[142:143], s[24:25], 0, v[134:135]
	s_mov_b32 m0, s48
	s_nop 0
	global_load_lds_dwordx4 v[142:143], off
	v_lshl_add_u64 v[250:251], s[24:25], 0, v[130:131]
	s_add_i32 m0, s48, 0x2000
	s_nop 0
	global_load_lds_dwordx4 v[250:251], off
	s_waitcnt vmcnt(6)
	s_barrier
	s_setprio 1
	v_add_u32_e32 v249, 0x10000, v167
	v_mfma_f32_16x16x32_bf16 v[54:57], v[222:225], v[190:193], v[54:57]
	ds_read_b128 v[142:145], v249
	ds_read_b128 v[162:165], v249 offset:1024
	v_mfma_f32_16x16x32_bf16 v[54:57], v[226:229], v[194:197], v[54:57]
	ds_read_b128 v[182:185], v249 offset:2048
	ds_read_b128 v[186:189], v249 offset:3072
	v_mfma_f32_16x16x32_bf16 v[50:53], v[230:233], v[190:193], v[50:53]
	ds_read_b128 v[190:193], v169
	v_mfma_f32_16x16x32_bf16 v[50:53], v[234:237], v[194:197], v[50:53]
	ds_read_b128 v[194:197], v169 offset:1024
	v_mfma_f32_16x16x32_bf16 v[38:41], v[222:225], v[198:201], v[38:41]
	v_mfma_f32_16x16x32_bf16 v[38:41], v[226:229], v[202:205], v[38:41]
	v_mfma_f32_16x16x32_bf16 v[34:37], v[230:233], v[198:201], v[34:37]
	ds_read_b128 v[198:201], v169 offset:2048
	v_mfma_f32_16x16x32_bf16 v[34:37], v[234:237], v[202:205], v[34:37]
	ds_read_b128 v[202:205], v169 offset:3072
	v_mfma_f32_16x16x32_bf16 v[22:25], v[222:225], v[206:209], v[22:25]
	v_mfma_f32_16x16x32_bf16 v[22:25], v[226:229], v[210:213], v[22:25]
	v_mfma_f32_16x16x32_bf16 v[18:21], v[230:233], v[206:209], v[18:21]
	ds_read_b128 v[206:209], v169 offset:4096
	v_mfma_f32_16x16x32_bf16 v[18:21], v[234:237], v[210:213], v[18:21]
	ds_read_b128 v[210:213], v169 offset:5120
	v_mfma_f32_16x16x32_bf16 v[6:9], v[222:225], v[214:217], v[6:9]
	v_mfma_f32_16x16x32_bf16 v[6:9], v[226:229], v[218:221], v[6:9]
	v_mfma_f32_16x16x32_bf16 v[2:5], v[230:233], v[214:217], v[2:5]
	s_barrier
	v_mfma_f32_16x16x32_bf16 v[2:5], v[234:237], v[218:221], v[2:5]
	s_setprio 0
	s_add_i32 s50, s50, 2
	s_add_u32 vcc_lo, vcc_lo, 0x100
	s_addc_u32 s35, s35, 0
	s_add_u32 s38, s38, 0x100
	s_addc_u32 s39, s39, 0
	s_cmp_gt_u32 s50, 13
	s_cbranch_scc0 .LBB0_165
	s_waitcnt lgkmcnt(0)
	s_and_b64 vcc, exec, s[40:41]
	s_cbranch_vccz .LBB0_168
	s_barrier

; #define PG8_STAGE(bufoff, gbase, voff) do { _Pragma("unroll") for (int _i = 0; _i < 2; ++_i) \
;         __builtin_amdgcn_global_load_lds((const unsigned*)((const char*)(gbase) + (voff)[_i]), (LAS unsigned*)(lds + (bufoff) + ldsw + _i * 8192), 16, 0, 0); } while (0)
; #define PG8_LDA(dst, b, h) do { _Pragma("unroll") for (int m = 0; m < 4; ++m) _Pragma("unroll") for (int k = 0; k < 2; ++k) dst[m][k] = *(const LAS bf16x8*)(lds + PG8_SA(b, h) + aoff + m * 2048 + k * 1024); } while (0)
; #define PG8_LDB(dst, b, h) do { _Pragma("unroll") for (int n = 0; n < 2; ++n) _Pragma("unroll") for (int k = 0; k < 2; ++k) dst[n][k] = *(const LAS bf16x8*)(lds + PG8_SB(b, h) + boff + n * 2048 + k * 1024); } while (0)
; #define PG8_SCHED __builtin_amdgcn_sched_barrier(0)
; template <class Epi, class Sched>
; __device__ __forceinline__ void gemm_phase(LAS unsigned char* lds, const Gemm g, const Sched& S, const Epi& E) {
;     ...
;         const bool has_next = S.next(ui + 1, nxt);
;         const char* nA = has_next ? PG8_APANEL(nxt.pm) : cA; const char* nB = has_next ? (const char*)g.Bt + (size_t)nxt.pn * tstep : cB;
;         for (int t = 0; t < nt; t += 2) {
;             const bool last = (t == nt - 2);
;             const char* a1 = cA + (size_t)(t + 1) * kstep;
;             const char* a2 = last ? nA : cA + (size_t)(t + 2) * kstep; const char* b2 = last ? nB : cB + (size_t)(t + 2) * kstep;
;             const char* a3 = a2 + kstep; const char* b3 = b2 + kstep;
;             PG8_LDB(B0, 0, 0); PG8_SCHED; PG8_LDA(At, 0, 0); PG8_STAGE(PG8_SA(1, 1), a1 + hstep, voffA);
;     ...
; #pragma unroll
;         for (int a = 0; a < 2; ++a)
; #pragma unroll
;             for (int b = 0; b < 2; ++b)
; #pragma unroll
;                 for (int m = 0; m < 4; ++m)
; #pragma unroll
;                     for (int n = 0; n < 2; ++n) acc[a][b][m][n] = (f32x4){0.f, 0.f, 0.f, 0.f};
;         cur = nxt; cA = nA; cB = nB; ++ui;
.LBB0_415:
	s_ashr_i32 s47, s46, 31
	s_lshl_b64 s[24:25], s[46:47], 19
	s_add_u32 s48, s82, s24
	s_addc_u32 s49, s83, s25
	s_and_b64 s[0:1], s[0:1], exec
	s_cselect_b32 s47, s49, s37
	s_cselect_b32 s61, s48, s36
	s_add_u32 s35, s36, 0x100
	s_addc_u32 s50, s37, 0
	s_add_u32 s0, s38, 0x40080
	v_mov_b32_e32 v2, 0
	s_addc_u32 s1, s39, 0
	s_mov_b32 s38, -2
	v_mov_b32_e32 v3, v2
	v_mov_b32_e32 v4, v2
	v_mov_b32_e32 v5, v2
	v_mov_b32_e32 v6, v2
	v_mov_b32_e32 v7, v2
	v_mov_b32_e32 v8, v2
	v_mov_b32_e32 v9, v2
	v_mov_b32_e32 v10, v2
	v_mov_b32_e32 v11, v2
	v_mov_b32_e32 v12, v2
	v_mov_b32_e32 v13, v2
	v_mov_b32_e32 v18, v2
	v_mov_b32_e32 v19, v2
	v_mov_b32_e32 v20, v2
	v_mov_b32_e32 v21, v2
	v_mov_b32_e32 v26, v2
	v_mov_b32_e32 v27, v2
	v_mov_b32_e32 v28, v2
	v_mov_b32_e32 v29, v2
	v_mov_b32_e32 v34, v2
	v_mov_b32_e32 v35, v2
	v_mov_b32_e32 v36, v2
	v_mov_b32_e32 v37, v2
	v_mov_b32_e32 v42, v2
	v_mov_b32_e32 v43, v2
	v_mov_b32_e32 v44, v2
	v_mov_b32_e32 v45, v2
	v_mov_b32_e32 v50, v2
	v_mov_b32_e32 v51, v2
	v_mov_b32_e32 v52, v2
	v_mov_b32_e32 v53, v2
	v_mov_b32_e32 v14, v2
	v_mov_b32_e32 v15, v2
	v_mov_b32_e32 v16, v2
	v_mov_b32_e32 v17, v2
	v_mov_b32_e32 v22, v2
	v_mov_b32_e32 v23, v2
	v_mov_b32_e32 v24, v2
	v_mov_b32_e32 v25, v2
	v_mov_b32_e32 v30, v2
	v_mov_b32_e32 v31, v2
	v_mov_b32_e32 v32, v2
	v_mov_b32_e32 v33, v2
	v_mov_b32_e32 v38, v2
	v_mov_b32_e32 v39, v2
	v_mov_b32_e32 v40, v2
	v_mov_b32_e32 v41, v2
	v_mov_b32_e32 v46, v2
	v_mov_b32_e32 v47, v2
	v_mov_b32_e32 v48, v2
	v_mov_b32_e32 v49, v2
	v_mov_b32_e32 v54, v2
	v_mov_b32_e32 v55, v2
	v_mov_b32_e32 v56, v2
	v_mov_b32_e32 v57, v2
	v_mov_b32_e32 v58, v2
	v_mov_b32_e32 v59, v2
	v_mov_b32_e32 v60, v2
	v_mov_b32_e32 v61, v2
	v_mov_b32_e32 v62, v2
	v_mov_b32_e32 v63, v2
	v_mov_b32_e32 v64, v2
	v_mov_b32_e32 v65, v2
	v_mov_b32_e32 v66, v2
	v_mov_b32_e32 v67, v2
	v_mov_b32_e32 v68, v2
	v_mov_b32_e32 v69, v2
	v_mov_b32_e32 v70, v2
	v_mov_b32_e32 v71, v2
	v_mov_b32_e32 v72, v2
	v_mov_b32_e32 v73, v2
	v_mov_b32_e32 v74, v2
	v_mov_b32_e32 v75, v2
	v_mov_b32_e32 v76, v2
	v_mov_b32_e32 v77, v2
	v_mov_b32_e32 v82, v2
	v_mov_b32_e32 v83, v2
	v_mov_b32_e32 v84, v2
	v_mov_b32_e32 v85, v2
	v_mov_b32_e32 v90, v2
	v_mov_b32_e32 v91, v2
	v_mov_b32_e32 v92, v2
	v_mov_b32_e32 v93, v2
	v_mov_b32_e32 v98, v2
	v_mov_b32_e32 v99, v2
	v_mov_b32_e32 v100, v2
	v_mov_b32_e32 v101, v2
	v_mov_b32_e32 v106, v2
	v_mov_b32_e32 v107, v2
	v_mov_b32_e32 v108, v2
	v_mov_b32_e32 v109, v2
	v_mov_b32_e32 v114, v2
	v_mov_b32_e32 v115, v2
	v_mov_b32_e32 v116, v2
	v_mov_b32_e32 v117, v2
	v_mov_b32_e32 v78, v2
	v_mov_b32_e32 v79, v2
	v_mov_b32_e32 v80, v2
	v_mov_b32_e32 v81, v2
	v_mov_b32_e32 v86, v2
	v_mov_b32_e32 v87, v2
	v_mov_b32_e32 v88, v2
	v_mov_b32_e32 v89, v2
	v_mov_b32_e32 v94, v2
	v_mov_b32_e32 v95, v2
	v_mov_b32_e32 v96, v2
	v_mov_b32_e32 v97, v2
	v_mov_b32_e32 v102, v2
	v_mov_b32_e32 v103, v2
	v_mov_b32_e32 v104, v2
	v_mov_b32_e32 v105, v2
	v_mov_b32_e32 v110, v2
	v_mov_b32_e32 v111, v2
	v_mov_b32_e32 v112, v2
	v_mov_b32_e32 v113, v2
	v_mov_b32_e32 v118, v2
	v_mov_b32_e32 v119, v2
	v_mov_b32_e32 v120, v2
	v_mov_b32_e32 v121, v2
	v_mov_b32_e32 v122, v2
	v_mov_b32_e32 v123, v2
	v_mov_b32_e32 v124, v2
	v_mov_b32_e32 v125, v2
	v_mov_b32_e32 v126, v2
	v_mov_b32_e32 v127, v2
	v_mov_b32_e32 v128, v2
	v_mov_b32_e32 v129, v2
	v_add_u32_e32 v249, 0x10000, v144
	ds_read_b128 v[164:167], v249
	ds_read_b128 v[182:185], v249 offset:1024
	ds_read_b128 v[186:189], v249 offset:2048
	ds_read_b128 v[190:193], v249 offset:3072
	ds_read_b128 v[194:197], v162
	ds_read_b128 v[198:201], v162 offset:1024
	ds_read_b128 v[202:205], v162 offset:2048
	ds_read_b128 v[206:209], v162 offset:3072
	ds_read_b128 v[210:213], v162 offset:4096
	ds_read_b128 v[214:217], v162 offset:5120
.LBB0_416:
	s_add_u32 s24, s0, 0xfffc0080
	s_addc_u32 s25, s1, -1
	s_add_i32 s39, 0, 0x10000
	v_add_u32_e32 v142, s39, v144
	s_cmp_eq_u32 s38, 12
	s_cselect_b32 vcc_hi, s77, s25
	s_cselect_b32 vcc_lo, s76, s24
	s_cselect_b32 s37, s47, s50
	s_cselect_b32 s36, s61, s35
	v_lshl_add_u64 v[142:143], s[0:1], 0, v[140:141]
	s_add_i32 m0, s93, 0xc000
	ds_read_b128 v[218:221], v162 offset:6144
	ds_read_b128 v[222:225], v162 offset:7168
	global_load_lds_dwordx4 v[142:143], off
	v_lshl_add_u64 v[250:251], s[0:1], 0, v[138:139]
	s_add_i32 m0, s93, 0xe000
	s_nop 0
	global_load_lds_dwordx4 v[250:251], off
	s_waitcnt lgkmcnt(8)
	s_barrier
	s_waitcnt lgkmcnt(0)
	s_setprio 1
	s_waitcnt lgkmcnt(0)
	v_mfma_f32_16x16x32_bf16 v[126:129], v[164:167], v[194:197], v[126:129]
	v_mfma_f32_16x16x32_bf16 v[126:129], v[182:185], v[198:201], v[126:129]
	v_mfma_f32_16x16x32_bf16 v[122:125], v[186:189], v[194:197], v[122:125]
	v_mfma_f32_16x16x32_bf16 v[122:125], v[190:193], v[198:201], v[122:125]
	v_mfma_f32_16x16x32_bf16 v[118:121], v[164:167], v[202:205], v[118:121]
	v_mfma_f32_16x16x32_bf16 v[118:121], v[182:185], v[206:209], v[118:121]
	v_mfma_f32_16x16x32_bf16 v[110:113], v[186:189], v[202:205], v[110:113]
	v_mfma_f32_16x16x32_bf16 v[110:113], v[190:193], v[206:209], v[110:113]
	v_mfma_f32_16x16x32_bf16 v[102:105], v[164:167], v[210:213], v[102:105]
	v_mfma_f32_16x16x32_bf16 v[102:105], v[182:185], v[214:217], v[102:105]
	v_mfma_f32_16x16x32_bf16 v[94:97], v[186:189], v[210:213], v[94:97]
	v_mfma_f32_16x16x32_bf16 v[94:97], v[190:193], v[214:217], v[94:97]
	v_mfma_f32_16x16x32_bf16 v[86:89], v[164:167], v[218:221], v[86:89]
	v_mfma_f32_16x16x32_bf16 v[86:89], v[182:185], v[222:225], v[86:89]
	v_mfma_f32_16x16x32_bf16 v[78:81], v[186:189], v[218:221], v[78:81]
	s_barrier
; #define PG8_STAGE(bufoff, gbase, voff) do { _Pragma("unroll") for (int _i = 0; _i < 2; ++_i) \
;         __builtin_amdgcn_global_load_lds((const unsigned*)((const char*)(gbase) + (voff)[_i]), (LAS unsigned*)(lds + (bufoff) + ldsw + _i * 8192), 16, 0, 0); } while (0)
; #define PG8_LDA(dst, b, h) do { _Pragma("unroll") for (int m = 0; m < 4; ++m) _Pragma("unroll") for (int k = 0; k < 2; ++k) dst[m][k] = *(const LAS bf16x8*)(lds + PG8_SA(b, h) + aoff + m * 2048 + k * 1024); } while (0)
; #define PG8_LDB(dst, b, h) do { _Pragma("unroll") for (int n = 0; n < 2; ++n) _Pragma("unroll") for (int k = 0; k < 2; ++k) dst[n][k] = *(const LAS bf16x8*)(lds + PG8_SB(b, h) + boff + n * 2048 + k * 1024); } while (0)
; #define PG8_MMA(ai, bj, At, Bt) do { __builtin_amdgcn_s_setprio(1); _Pragma("unroll") for (int m = 0; m < 4; ++m) _Pragma("unroll") for (int n = 0; n < 2; ++n) _Pragma("unroll") for (int k = 0; k < 2; ++k) \
;         acc[ai][bj][m][n] = __builtin_amdgcn_mfma_f32_16x16x32_bf16(Bt[n][k], At[m][k], acc[ai][bj][m][n], 0, 0, 0); __builtin_amdgcn_s_setprio(0); } while (0)
; #define PG8_WAIT_V(n) asm volatile("s_waitcnt vmcnt(" #n ")" ::: "memory")
; #define PG8_WAIT_L(n) asm volatile("s_waitcnt lgkmcnt(" #n ")" ::: "memory")
; #define PG8_BAR __builtin_amdgcn_s_barrier()
; #define PG8_SCHED __builtin_amdgcn_sched_barrier(0)
; template <class Epi, class Sched>
; __device__ __forceinline__ void gemm_phase(LAS unsigned char* lds, const Gemm g, const Sched& S, const Epi& E) {
;     ...
;             PG8_WAIT_L(8); PG8_BAR; PG8_WAIT_L(0); PG8_MMA(0, 0, At, B0); PG8_BAR; PG8_SCHED;
;             PG8_LDB(B1, 0, 1); PG8_STAGE(PG8_SB(0, 0), b2, voffB);
;             PG8_BAR; PG8_WAIT_L(0); PG8_MMA(0, 1, At, B1); PG8_BAR;
;             PG8_LDA(At, 0, 1); PG8_STAGE(PG8_SA(0, 0), a2, voffA);
;             PG8_BAR; PG8_WAIT_L(0); PG8_MMA(1, 0, At, B0); PG8_BAR; PG8_SCHED;
;             PG8_STAGE(PG8_SB(0, 1), b2 + hstep, voffB);
;             PG8_WAIT_V(6); PG8_BAR; PG8_MMA(1, 1, At, B1); PG8_BAR;
;             PG8_LDB(B0, 1, 0); PG8_SCHED; PG8_LDA(At, 1, 0); PG8_STAGE(PG8_SA(0, 1), a2 + hstep, voffA);
;             PG8_WAIT_L(8); PG8_BAR; PG8_WAIT_L(0); PG8_MMA(0, 0, At, B0); PG8_BAR; PG8_SCHED;
	v_mfma_f32_16x16x32_bf16 v[78:81], v[190:193], v[222:225], v[78:81]
	s_setprio 0
	s_add_i32 s51, 0, 0x14000
	v_add_u32_e32 v142, s51, v144
	s_add_i32 s24, s39, s86
	ds_read_b128 v[226:229], v142
	ds_read_b128 v[230:233], v142 offset:1024
	ds_read_b128 v[234:237], v142 offset:2048
	ds_read_b128 v[238:241], v142 offset:3072
	v_lshl_add_u64 v[142:143], s[36:37], 0, v[134:135]
	s_mov_b32 m0, s24
	v_lshl_add_u64 v[168:169], s[36:37], 0, v[130:131]
	global_load_lds_dwordx4 v[142:143], off
	s_add_i32 m0, s24, 0x2000
	s_nop 0
	global_load_lds_dwordx4 v[168:169], off
	s_barrier
	s_waitcnt lgkmcnt(0)
	s_setprio 1
	s_waitcnt lgkmcnt(0)
	v_mfma_f32_16x16x32_bf16 v[114:117], v[226:229], v[194:197], v[114:117]
	v_mfma_f32_16x16x32_bf16 v[114:117], v[230:233], v[198:201], v[114:117]
	v_mfma_f32_16x16x32_bf16 v[106:109], v[234:237], v[194:197], v[106:109]
	v_mfma_f32_16x16x32_bf16 v[106:109], v[238:241], v[198:201], v[106:109]
	v_mfma_f32_16x16x32_bf16 v[98:101], v[226:229], v[202:205], v[98:101]
	v_mfma_f32_16x16x32_bf16 v[98:101], v[230:233], v[206:209], v[98:101]
	v_mfma_f32_16x16x32_bf16 v[90:93], v[234:237], v[202:205], v[90:93]
	v_mfma_f32_16x16x32_bf16 v[90:93], v[238:241], v[206:209], v[90:93]
	v_mfma_f32_16x16x32_bf16 v[82:85], v[226:229], v[210:213], v[82:85]
	v_mfma_f32_16x16x32_bf16 v[82:85], v[230:233], v[214:217], v[82:85]
	v_mfma_f32_16x16x32_bf16 v[74:77], v[234:237], v[210:213], v[74:77]
	v_mfma_f32_16x16x32_bf16 v[74:77], v[238:241], v[214:217], v[74:77]
	v_mfma_f32_16x16x32_bf16 v[70:73], v[226:229], v[218:221], v[70:73]
	v_mfma_f32_16x16x32_bf16 v[70:73], v[230:233], v[222:225], v[70:73]
	v_mfma_f32_16x16x32_bf16 v[66:69], v[234:237], v[218:221], v[66:69]
	s_barrier
	v_mfma_f32_16x16x32_bf16 v[66:69], v[238:241], v[222:225], v[66:69]
	s_setprio 0
	s_mov_b32 m0, s93
	v_lshl_add_u64 v[242:243], vcc, 0, v[136:137]
	ds_read_b128 v[194:197], v162 offset:16384
	ds_read_b128 v[198:201], v162 offset:17408
	ds_read_b128 v[202:205], v162 offset:18432
	ds_read_b128 v[206:209], v162 offset:19456
	ds_read_b128 v[210:213], v162 offset:20480
	ds_read_b128 v[214:217], v162 offset:21504
	ds_read_b128 v[218:221], v162 offset:22528
	ds_read_b128 v[222:225], v162 offset:23552
	global_load_lds_dwordx4 v[242:243], off
	v_lshl_add_u64 v[244:245], vcc, 0, v[132:133]
	s_mov_b32 m0, s94
	s_nop 0
	global_load_lds_dwordx4 v[244:245], off
	s_waitcnt vmcnt(8)
	s_barrier
	s_waitcnt lgkmcnt(0)
	s_setprio 1
	s_waitcnt lgkmcnt(0)
	v_mfma_f32_16x16x32_bf16 v[62:65], v[164:167], v[194:197], v[62:65]
	v_mfma_f32_16x16x32_bf16 v[62:65], v[182:185], v[198:201], v[62:65]
	v_mfma_f32_16x16x32_bf16 v[58:61], v[186:189], v[194:197], v[58:61]
	v_mfma_f32_16x16x32_bf16 v[58:61], v[190:193], v[198:201], v[58:61]
	v_mfma_f32_16x16x32_bf16 v[54:57], v[164:167], v[202:205], v[54:57]
	v_mfma_f32_16x16x32_bf16 v[54:57], v[182:185], v[206:209], v[54:57]
	v_mfma_f32_16x16x32_bf16 v[46:49], v[186:189], v[202:205], v[46:49]
	v_mfma_f32_16x16x32_bf16 v[46:49], v[190:193], v[206:209], v[46:49]
	v_mfma_f32_16x16x32_bf16 v[38:41], v[164:167], v[210:213], v[38:41]
	v_mfma_f32_16x16x32_bf16 v[38:41], v[182:185], v[214:217], v[38:41]
	v_mfma_f32_16x16x32_bf16 v[30:33], v[186:189], v[210:213], v[30:33]
	v_mfma_f32_16x16x32_bf16 v[30:33], v[190:193], v[214:217], v[30:33]
	v_mfma_f32_16x16x32_bf16 v[22:25], v[164:167], v[218:221], v[22:25]
	v_mfma_f32_16x16x32_bf16 v[22:25], v[182:185], v[222:225], v[22:25]
	v_mfma_f32_16x16x32_bf16 v[14:17], v[186:189], v[218:221], v[14:17]
	s_barrier
	v_mfma_f32_16x16x32_bf16 v[14:17], v[190:193], v[222:225], v[14:17]
	s_setprio 0
	s_add_u32 s24, s36, 0x40000
	s_addc_u32 s25, s37, 0
	s_add_i32 s39, s51, s86
	v_lshl_add_u64 v[164:165], s[24:25], 0, v[134:135]
	s_mov_b32 m0, s39
	s_nop 0
	global_load_lds_dwordx4 v[164:165], off
	v_lshl_add_u64 v[250:251], s[24:25], 0, v[130:131]
	s_add_i32 m0, s39, 0x2000
	s_nop 0
	global_load_lds_dwordx4 v[250:251], off
	s_waitcnt vmcnt(6)
	s_barrier
	s_setprio 1
	v_add_u32_e32 v249, 0x18000, v144
	v_mfma_f32_16x16x32_bf16 v[50:53], v[226:229], v[194:197], v[50:53]
	ds_read_b128 v[164:167], v249
	ds_read_b128 v[182:185], v249 offset:1024
	v_mfma_f32_16x16x32_bf16 v[50:53], v[230:233], v[198:201], v[50:53]
	ds_read_b128 v[186:189], v249 offset:2048
	ds_read_b128 v[190:193], v249 offset:3072
	v_mfma_f32_16x16x32_bf16 v[42:45], v[234:237], v[194:197], v[42:45]
	ds_read_b128 v[194:197], v162 offset:32768
	v_mfma_f32_16x16x32_bf16 v[42:45], v[238:241], v[198:201], v[42:45]
	ds_read_b128 v[198:201], v162 offset:33792
	v_mfma_f32_16x16x32_bf16 v[34:37], v[226:229], v[202:205], v[34:37]
	v_mfma_f32_16x16x32_bf16 v[34:37], v[230:233], v[206:209], v[34:37]
	v_mfma_f32_16x16x32_bf16 v[26:29], v[234:237], v[202:205], v[26:29]
	ds_read_b128 v[202:205], v162 offset:34816
	v_mfma_f32_16x16x32_bf16 v[26:29], v[238:241], v[206:209], v[26:29]
	ds_read_b128 v[206:209], v162 offset:35840
	v_mfma_f32_16x16x32_bf16 v[18:21], v[226:229], v[210:213], v[18:21]
	v_mfma_f32_16x16x32_bf16 v[18:21], v[230:233], v[214:217], v[18:21]
	v_mfma_f32_16x16x32_bf16 v[10:13], v[234:237], v[210:213], v[10:13]
	ds_read_b128 v[210:213], v162 offset:36864
	v_mfma_f32_16x16x32_bf16 v[10:13], v[238:241], v[214:217], v[10:13]
	ds_read_b128 v[214:217], v162 offset:37888
	v_mfma_f32_16x16x32_bf16 v[6:9], v[226:229], v[218:221], v[6:9]
	v_mfma_f32_16x16x32_bf16 v[6:9], v[230:233], v[222:225], v[6:9]
	v_mfma_f32_16x16x32_bf16 v[2:5], v[234:237], v[218:221], v[2:5]
	s_barrier
; #define PG8_STAGE(bufoff, gbase, voff) do { _Pragma("unroll") for (int _i = 0; _i < 2; ++_i) \
;         __builtin_amdgcn_global_load_lds((const unsigned*)((const char*)(gbase) + (voff)[_i]), (LAS unsigned*)(lds + (bufoff) + ldsw + _i * 8192), 16, 0, 0); } while (0)
; #define PG8_LDA(dst, b, h) do { _Pragma("unroll") for (int m = 0; m < 4; ++m) _Pragma("unroll") for (int k = 0; k < 2; ++k) dst[m][k] = *(const LAS bf16x8*)(lds + PG8_SA(b, h) + aoff + m * 2048 + k * 1024); } while (0)
; #define PG8_LDB(dst, b, h) do { _Pragma("unroll") for (int n = 0; n < 2; ++n) _Pragma("unroll") for (int k = 0; k < 2; ++k) dst[n][k] = *(const LAS bf16x8*)(lds + PG8_SB(b, h) + boff + n * 2048 + k * 1024); } while (0)
; #define PG8_MMA(ai, bj, At, Bt) do { __builtin_amdgcn_s_setprio(1); _Pragma("unroll") for (int m = 0; m < 4; ++m) _Pragma("unroll") for (int n = 0; n < 2; ++n) _Pragma("unroll") for (int k = 0; k < 2; ++k) \
;         acc[ai][bj][m][n] = __builtin_amdgcn_mfma_f32_16x16x32_bf16(Bt[n][k], At[m][k], acc[ai][bj][m][n], 0, 0, 0); __builtin_amdgcn_s_setprio(0); } while (0)
; #define PG8_WAIT_L(n) asm volatile("s_waitcnt lgkmcnt(" #n ")" ::: "memory")
; #define PG8_BAR __builtin_amdgcn_s_barrier()
; #define PG8_SCHED __builtin_amdgcn_sched_barrier(0)
; template <class Epi, class Sched>
; __device__ __forceinline__ void gemm_phase(LAS unsigned char* lds, const Gemm g, const Sched& S, const Epi& E) {
;     ...
;             PG8_LDB(B0, 1, 0); PG8_SCHED; PG8_LDA(At, 1, 0); PG8_STAGE(PG8_SA(0, 1), a2 + hstep, voffA);
;             PG8_WAIT_L(8); PG8_BAR; PG8_WAIT_L(0); PG8_MMA(0, 0, At, B0); PG8_BAR; PG8_SCHED;
;             PG8_LDB(B1, 1, 1); PG8_STAGE(PG8_SB(1, 0), b3, voffB);
;             PG8_BAR; PG8_WAIT_L(0); PG8_MMA(0, 1, At, B1); PG8_BAR;
	v_mfma_f32_16x16x32_bf16 v[2:5], v[238:241], v[222:225], v[2:5]
	s_setprio 0
	s_add_i32 s39, 0, 0x18000
	v_add_u32_e32 v163, s39, v144
	s_add_u32 s24, vcc_lo, 0x40000
	s_addc_u32 s25, vcc_hi, 0
	s_mov_b32 m0, s95
	v_lshl_add_u64 v[226:227], s[24:25], 0, v[136:137]
	ds_read_b128 v[218:221], v162 offset:38912
	ds_read_b128 v[222:225], v162 offset:39936
	global_load_lds_dwordx4 v[226:227], off
	v_lshl_add_u64 v[250:251], s[24:25], 0, v[132:133]
	s_mov_b32 m0, s96
	s_nop 0
	global_load_lds_dwordx4 v[250:251], off
	s_waitcnt lgkmcnt(8)
	s_barrier
	s_waitcnt lgkmcnt(0)
	s_setprio 1
	s_waitcnt lgkmcnt(0)
	v_mfma_f32_16x16x32_bf16 v[126:129], v[164:167], v[194:197], v[126:129]
	v_mfma_f32_16x16x32_bf16 v[126:129], v[182:185], v[198:201], v[126:129]
	v_mfma_f32_16x16x32_bf16 v[122:125], v[186:189], v[194:197], v[122:125]
	v_mfma_f32_16x16x32_bf16 v[122:125], v[190:193], v[198:201], v[122:125]
	v_mfma_f32_16x16x32_bf16 v[118:121], v[164:167], v[202:205], v[118:121]
	v_mfma_f32_16x16x32_bf16 v[118:121], v[182:185], v[206:209], v[118:121]
	v_mfma_f32_16x16x32_bf16 v[110:113], v[186:189], v[202:205], v[110:113]
	v_mfma_f32_16x16x32_bf16 v[110:113], v[190:193], v[206:209], v[110:113]
	v_mfma_f32_16x16x32_bf16 v[102:105], v[164:167], v[210:213], v[102:105]
	v_mfma_f32_16x16x32_bf16 v[102:105], v[182:185], v[214:217], v[102:105]
	v_mfma_f32_16x16x32_bf16 v[94:97], v[186:189], v[210:213], v[94:97]
	v_mfma_f32_16x16x32_bf16 v[94:97], v[190:193], v[214:217], v[94:97]
	v_mfma_f32_16x16x32_bf16 v[86:89], v[164:167], v[218:221], v[86:89]
	v_mfma_f32_16x16x32_bf16 v[86:89], v[182:185], v[222:225], v[86:89]
	v_mfma_f32_16x16x32_bf16 v[78:81], v[186:189], v[218:221], v[78:81]
	s_barrier
	v_mfma_f32_16x16x32_bf16 v[78:81], v[190:193], v[222:225], v[78:81]
	s_setprio 0
	s_add_i32 s51, 0, 0x1c000
	s_add_i32 s24, s39, s86
	v_add_u32_e32 v163, s51, v144
	v_lshl_add_u64 v[142:143], v[142:143], 0, s[12:13]
	s_mov_b32 m0, s24
	ds_read_b128 v[226:229], v163
	ds_read_b128 v[230:233], v163 offset:1024
	ds_read_b128 v[234:237], v163 offset:2048
	ds_read_b128 v[238:241], v163 offset:3072
	global_load_lds_dwordx4 v[142:143], off
	v_lshl_add_u64 v[250:251], v[168:169], 0, s[12:13]
	s_add_i32 m0, s24, 0x2000
	s_nop 0
	global_load_lds_dwordx4 v[250:251], off
	s_barrier
	s_waitcnt lgkmcnt(0)
	s_setprio 1
	s_waitcnt lgkmcnt(0)
	v_mfma_f32_16x16x32_bf16 v[114:117], v[226:229], v[194:197], v[114:117]
	v_mfma_f32_16x16x32_bf16 v[114:117], v[230:233], v[198:201], v[114:117]
	v_mfma_f32_16x16x32_bf16 v[106:109], v[234:237], v[194:197], v[106:109]
	v_mfma_f32_16x16x32_bf16 v[106:109], v[238:241], v[198:201], v[106:109]
	v_mfma_f32_16x16x32_bf16 v[98:101], v[226:229], v[202:205], v[98:101]
	v_mfma_f32_16x16x32_bf16 v[98:101], v[230:233], v[206:209], v[98:101]
	v_mfma_f32_16x16x32_bf16 v[90:93], v[234:237], v[202:205], v[90:93]
	v_mfma_f32_16x16x32_bf16 v[90:93], v[238:241], v[206:209], v[90:93]
	v_mfma_f32_16x16x32_bf16 v[82:85], v[226:229], v[210:213], v[82:85]
	v_mfma_f32_16x16x32_bf16 v[82:85], v[230:233], v[214:217], v[82:85]
	v_mfma_f32_16x16x32_bf16 v[74:77], v[234:237], v[210:213], v[74:77]
	v_mfma_f32_16x16x32_bf16 v[74:77], v[238:241], v[214:217], v[74:77]
	v_mfma_f32_16x16x32_bf16 v[70:73], v[226:229], v[218:221], v[70:73]
	v_mfma_f32_16x16x32_bf16 v[70:73], v[230:233], v[222:225], v[70:73]
	v_mfma_f32_16x16x32_bf16 v[66:69], v[234:237], v[218:221], v[66:69]
	s_barrier
; #define PG8_STAGE(bufoff, gbase, voff) do { _Pragma("unroll") for (int _i = 0; _i < 2; ++_i) \
;         __builtin_amdgcn_global_load_lds((const unsigned*)((const char*)(gbase) + (voff)[_i]), (LAS unsigned*)(lds + (bufoff) + ldsw + _i * 8192), 16, 0, 0); } while (0)
; #define PG8_LDA(dst, b, h) do { _Pragma("unroll") for (int m = 0; m < 4; ++m) _Pragma("unroll") for (int k = 0; k < 2; ++k) dst[m][k] = *(const LAS bf16x8*)(lds + PG8_SA(b, h) + aoff + m * 2048 + k * 1024); } while (0)
; #define PG8_LDB(dst, b, h) do { _Pragma("unroll") for (int n = 0; n < 2; ++n) _Pragma("unroll") for (int k = 0; k < 2; ++k) dst[n][k] = *(const LAS bf16x8*)(lds + PG8_SB(b, h) + boff + n * 2048 + k * 1024); } while (0)
; #define PG8_MMA(ai, bj, At, Bt) do { __builtin_amdgcn_s_setprio(1); _Pragma("unroll") for (int m = 0; m < 4; ++m) _Pragma("unroll") for (int n = 0; n < 2; ++n) _Pragma("unroll") for (int k = 0; k < 2; ++k) \
;         acc[ai][bj][m][n] = __builtin_amdgcn_mfma_f32_16x16x32_bf16(Bt[n][k], At[m][k], acc[ai][bj][m][n], 0, 0, 0); __builtin_amdgcn_s_setprio(0); } while (0)
; #define PG8_WAIT_V(n) asm volatile("s_waitcnt vmcnt(" #n ")" ::: "memory")
; #define PG8_WAIT_L(n) asm volatile("s_waitcnt lgkmcnt(" #n ")" ::: "memory")
; #define PG8_BAR __builtin_amdgcn_s_barrier()
; #define PG8_SCHED __builtin_amdgcn_sched_barrier(0)
; template <class Epi, class Sched>
; __device__ __forceinline__ void gemm_phase(LAS unsigned char* lds, const Gemm g, const Sched& S, const Epi& E) {
;     ...
;             PG8_LDB(B1, 1, 1); PG8_STAGE(PG8_SB(1, 0), b3, voffB);
;             PG8_BAR; PG8_WAIT_L(0); PG8_MMA(0, 1, At, B1); PG8_BAR;
;             PG8_LDA(At, 1, 1); PG8_STAGE(PG8_SA(1, 0), a3, voffA);
;             PG8_BAR; PG8_WAIT_L(0); PG8_MMA(1, 0, At, B0); PG8_BAR; PG8_SCHED;
;             PG8_STAGE(PG8_SB(1, 1), b3 + hstep, voffB);
;             PG8_WAIT_V(6); PG8_BAR; PG8_MMA(1, 1, At, B1); PG8_BAR;
;         }
;         if (wr == 0) PG8_BAR;
	v_mfma_f32_16x16x32_bf16 v[66:69], v[238:241], v[222:225], v[66:69]
	s_setprio 0
	s_mov_b32 m0, s97
	v_lshl_add_u64 v[142:143], v[242:243], 0, s[12:13]
	ds_read_b128 v[194:197], v162 offset:49152
	ds_read_b128 v[198:201], v162 offset:50176
	ds_read_b128 v[202:205], v162 offset:51200
	ds_read_b128 v[206:209], v162 offset:52224
	ds_read_b128 v[210:213], v162 offset:53248
	ds_read_b128 v[214:217], v162 offset:54272
	ds_read_b128 v[218:221], v162 offset:55296
	ds_read_b128 v[222:225], v162 offset:56320
	global_load_lds_dwordx4 v[142:143], off
	v_lshl_add_u64 v[250:251], v[244:245], 0, s[12:13]
	s_mov_b32 m0, s98
	s_nop 0
	global_load_lds_dwordx4 v[250:251], off
	s_waitcnt vmcnt(8)
	s_barrier
	s_waitcnt lgkmcnt(0)
	s_setprio 1
	s_waitcnt lgkmcnt(0)
	v_mfma_f32_16x16x32_bf16 v[62:65], v[164:167], v[194:197], v[62:65]
	v_mfma_f32_16x16x32_bf16 v[62:65], v[182:185], v[198:201], v[62:65]
	v_mfma_f32_16x16x32_bf16 v[58:61], v[186:189], v[194:197], v[58:61]
	v_mfma_f32_16x16x32_bf16 v[58:61], v[190:193], v[198:201], v[58:61]
	v_mfma_f32_16x16x32_bf16 v[54:57], v[164:167], v[202:205], v[54:57]
	v_mfma_f32_16x16x32_bf16 v[54:57], v[182:185], v[206:209], v[54:57]
	v_mfma_f32_16x16x32_bf16 v[46:49], v[186:189], v[202:205], v[46:49]
	v_mfma_f32_16x16x32_bf16 v[46:49], v[190:193], v[206:209], v[46:49]
	v_mfma_f32_16x16x32_bf16 v[38:41], v[164:167], v[210:213], v[38:41]
	v_mfma_f32_16x16x32_bf16 v[38:41], v[182:185], v[214:217], v[38:41]
	v_mfma_f32_16x16x32_bf16 v[30:33], v[186:189], v[210:213], v[30:33]
	v_mfma_f32_16x16x32_bf16 v[30:33], v[190:193], v[214:217], v[30:33]
	v_mfma_f32_16x16x32_bf16 v[22:25], v[164:167], v[218:221], v[22:25]
	v_mfma_f32_16x16x32_bf16 v[22:25], v[182:185], v[222:225], v[22:25]
	v_mfma_f32_16x16x32_bf16 v[14:17], v[186:189], v[218:221], v[14:17]
	s_barrier
	v_mfma_f32_16x16x32_bf16 v[14:17], v[190:193], v[222:225], v[14:17]
	s_setprio 0
	s_add_u32 s24, s36, 0x40080
	s_addc_u32 s25, s37, 0
	s_add_i32 s36, s51, s86
	v_lshl_add_u64 v[142:143], s[24:25], 0, v[134:135]
	s_mov_b32 m0, s36
	s_nop 0
	global_load_lds_dwordx4 v[142:143], off
	v_lshl_add_u64 v[250:251], s[24:25], 0, v[130:131]
	s_add_i32 m0, s36, 0x2000
	s_nop 0
	global_load_lds_dwordx4 v[250:251], off
	s_waitcnt vmcnt(6)
	s_barrier
	s_setprio 1
	v_add_u32_e32 v249, 0x10000, v144
	v_mfma_f32_16x16x32_bf16 v[50:53], v[226:229], v[194:197], v[50:53]
	ds_read_b128 v[164:167], v249
	ds_read_b128 v[182:185], v249 offset:1024
	v_mfma_f32_16x16x32_bf16 v[50:53], v[230:233], v[198:201], v[50:53]
	ds_read_b128 v[186:189], v249 offset:2048
	ds_read_b128 v[190:193], v249 offset:3072
	v_mfma_f32_16x16x32_bf16 v[42:45], v[234:237], v[194:197], v[42:45]
	ds_read_b128 v[194:197], v162
	v_mfma_f32_16x16x32_bf16 v[42:45], v[238:241], v[198:201], v[42:45]
	ds_read_b128 v[198:201], v162 offset:1024
	v_mfma_f32_16x16x32_bf16 v[34:37], v[226:229], v[202:205], v[34:37]
	v_mfma_f32_16x16x32_bf16 v[34:37], v[230:233], v[206:209], v[34:37]
	v_mfma_f32_16x16x32_bf16 v[26:29], v[234:237], v[202:205], v[26:29]
	ds_read_b128 v[202:205], v162 offset:2048
	v_mfma_f32_16x16x32_bf16 v[26:29], v[238:241], v[206:209], v[26:29]
	ds_read_b128 v[206:209], v162 offset:3072
	v_mfma_f32_16x16x32_bf16 v[18:21], v[226:229], v[210:213], v[18:21]
	v_mfma_f32_16x16x32_bf16 v[18:21], v[230:233], v[214:217], v[18:21]
	v_mfma_f32_16x16x32_bf16 v[10:13], v[234:237], v[210:213], v[10:13]
	ds_read_b128 v[210:213], v162 offset:4096
	v_mfma_f32_16x16x32_bf16 v[10:13], v[238:241], v[214:217], v[10:13]
	ds_read_b128 v[214:217], v162 offset:5120
	v_mfma_f32_16x16x32_bf16 v[6:9], v[226:229], v[218:221], v[6:9]
	v_mfma_f32_16x16x32_bf16 v[6:9], v[230:233], v[222:225], v[6:9]
	v_mfma_f32_16x16x32_bf16 v[2:5], v[234:237], v[218:221], v[2:5]
	s_barrier
	v_mfma_f32_16x16x32_bf16 v[2:5], v[238:241], v[222:225], v[2:5]
	s_setprio 0
	s_add_i32 s38, s38, 2
	s_add_u32 s35, s35, 0x100
	s_addc_u32 s50, s50, 0
	s_add_u32 s0, s0, 0x100
	s_addc_u32 s1, s1, 0
	s_cmp_gt_u32 s38, 13
	s_cbranch_scc0 .LBB0_416
	s_waitcnt lgkmcnt(0)
	s_and_b64 vcc, exec, s[44:45]
	s_cbranch_vccz .LBB0_419
	s_barrier

; #define PG8_STAGE(bufoff, gbase, voff) do { _Pragma("unroll") for (int _i = 0; _i < 2; ++_i) \
;         __builtin_amdgcn_global_load_lds((const unsigned*)((const char*)(gbase) + (voff)[_i]), (LAS unsigned*)(lds + (bufoff) + ldsw + _i * 8192), 16, 0, 0); } while (0)
; #define PG8_LDA(dst, b, h) do { _Pragma("unroll") for (int m = 0; m < 4; ++m) _Pragma("unroll") for (int k = 0; k < 2; ++k) dst[m][k] = *(const LAS bf16x8*)(lds + PG8_SA(b, h) + aoff + m * 2048 + k * 1024); } while (0)
; #define PG8_LDB(dst, b, h) do { _Pragma("unroll") for (int n = 0; n < 2; ++n) _Pragma("unroll") for (int k = 0; k < 2; ++k) dst[n][k] = *(const LAS bf16x8*)(lds + PG8_SB(b, h) + boff + n * 2048 + k * 1024); } while (0)
; #define PG8_MMA(ai, bj, At, Bt) do { __builtin_amdgcn_s_setprio(1); _Pragma("unroll") for (int m = 0; m < 4; ++m) _Pragma("unroll") for (int n = 0; n < 2; ++n) _Pragma("unroll") for (int k = 0; k < 2; ++k) \
;         acc[ai][bj][m][n] = __builtin_amdgcn_mfma_f32_16x16x32_bf16(Bt[n][k], At[m][k], acc[ai][bj][m][n], 0, 0, 0); __builtin_amdgcn_s_setprio(0); } while (0)
; #define PG8_BAR __builtin_amdgcn_s_barrier()
; template <class Epi, class Sched>
; __device__ __forceinline__ void gemm_phase(LAS unsigned char* lds, const Gemm g, const Sched& S, const Epi& E) {
;     ...
;         const bool has_next = S.next(ui + 1, nxt);
;         const char* nA = has_next ? PG8_APANEL(nxt.pm) : cA; const char* nB = has_next ? (const char*)g.Bt + (size_t)nxt.pn * tstep : cB;
;         for (int t = 0; t < nt; t += 2) {
;             const bool last = (t == nt - 2);
;             const char* a1 = cA + (size_t)(t + 1) * kstep;
;             const char* a2 = last ? nA : cA + (size_t)(t + 2) * kstep; const char* b2 = last ? nB : cB + (size_t)(t + 2) * kstep;
;             const char* a3 = a2 + kstep; const char* b3 = b2 + kstep;
;             PG8_LDB(B0, 0, 0); PG8_SCHED; PG8_LDA(At, 0, 0); PG8_STAGE(PG8_SA(1, 1), a1 + hstep, voffA);
;             PG8_WAIT_L(8); PG8_BAR; PG8_WAIT_L(0); PG8_MMA(0, 0, At, B0); PG8_BAR; PG8_SCHED;
;     ...
; #pragma unroll
;         for (int a = 0; a < 2; ++a)
; #pragma unroll
;             for (int b = 0; b < 2; ++b)
; #pragma unroll
;                 for (int m = 0; m < 4; ++m)
; #pragma unroll
;                     for (int n = 0; n < 2; ++n) acc[a][b][m][n] = (f32x4){0.f, 0.f, 0.f, 0.f};
;         cur = nxt; cA = nA; cB = nB; ++ui;
.LBB0_556:
	s_ashr_i32 s45, s44, 31
	s_lshl_b64 s[24:25], s[44:45], 19
	s_add_u32 s60, s86, s24
	s_addc_u32 s61, s93, s25
	s_and_b64 s[0:1], s[0:1], exec
	s_cselect_b32 s45, s61, s49
	s_cselect_b32 s47, s60, s48
	s_add_u32 s35, s48, 0x100
	s_addc_u32 s50, s49, 0
	s_add_u32 s0, s38, 0x40080
	v_mov_b32_e32 v2, 0
	s_addc_u32 s1, s39, 0
	s_mov_b32 s38, -2
	v_mov_b32_e32 v3, v2
	v_mov_b32_e32 v4, v2
	v_mov_b32_e32 v5, v2
	v_mov_b32_e32 v6, v2
	v_mov_b32_e32 v7, v2
	v_mov_b32_e32 v8, v2
	v_mov_b32_e32 v9, v2
	v_mov_b32_e32 v18, v2
	v_mov_b32_e32 v19, v2
	v_mov_b32_e32 v20, v2
	v_mov_b32_e32 v21, v2
	v_mov_b32_e32 v22, v2
	v_mov_b32_e32 v23, v2
	v_mov_b32_e32 v24, v2
	v_mov_b32_e32 v25, v2
	v_mov_b32_e32 v34, v2
	v_mov_b32_e32 v35, v2
	v_mov_b32_e32 v36, v2
	v_mov_b32_e32 v37, v2
	v_mov_b32_e32 v38, v2
	v_mov_b32_e32 v39, v2
	v_mov_b32_e32 v40, v2
	v_mov_b32_e32 v41, v2
	v_mov_b32_e32 v50, v2
	v_mov_b32_e32 v51, v2
	v_mov_b32_e32 v52, v2
	v_mov_b32_e32 v53, v2
	v_mov_b32_e32 v54, v2
	v_mov_b32_e32 v55, v2
	v_mov_b32_e32 v56, v2
	v_mov_b32_e32 v57, v2
	v_mov_b32_e32 v10, v2
	v_mov_b32_e32 v11, v2
	v_mov_b32_e32 v12, v2
	v_mov_b32_e32 v13, v2
	v_mov_b32_e32 v14, v2
	v_mov_b32_e32 v15, v2
	v_mov_b32_e32 v16, v2
	v_mov_b32_e32 v17, v2
	v_mov_b32_e32 v26, v2
	v_mov_b32_e32 v27, v2
	v_mov_b32_e32 v28, v2
	v_mov_b32_e32 v29, v2
	v_mov_b32_e32 v30, v2
	v_mov_b32_e32 v31, v2
	v_mov_b32_e32 v32, v2
	v_mov_b32_e32 v33, v2
	v_mov_b32_e32 v42, v2
	v_mov_b32_e32 v43, v2
	v_mov_b32_e32 v44, v2
	v_mov_b32_e32 v45, v2
	v_mov_b32_e32 v46, v2
	v_mov_b32_e32 v47, v2
	v_mov_b32_e32 v48, v2
	v_mov_b32_e32 v49, v2
	v_mov_b32_e32 v58, v2
	v_mov_b32_e32 v59, v2
	v_mov_b32_e32 v60, v2
	v_mov_b32_e32 v61, v2
	v_mov_b32_e32 v62, v2
	v_mov_b32_e32 v63, v2
	v_mov_b32_e32 v64, v2
	v_mov_b32_e32 v65, v2
	v_mov_b32_e32 v66, v2
	v_mov_b32_e32 v67, v2
	v_mov_b32_e32 v68, v2
	v_mov_b32_e32 v69, v2
	v_mov_b32_e32 v70, v2
	v_mov_b32_e32 v71, v2
	v_mov_b32_e32 v72, v2
	v_mov_b32_e32 v73, v2
	v_mov_b32_e32 v82, v2
	v_mov_b32_e32 v83, v2
	v_mov_b32_e32 v84, v2
	v_mov_b32_e32 v85, v2
	v_mov_b32_e32 v86, v2
	v_mov_b32_e32 v87, v2
	v_mov_b32_e32 v88, v2
	v_mov_b32_e32 v89, v2
	v_mov_b32_e32 v98, v2
	v_mov_b32_e32 v99, v2
	v_mov_b32_e32 v100, v2
	v_mov_b32_e32 v101, v2
	v_mov_b32_e32 v102, v2
	v_mov_b32_e32 v103, v2
	v_mov_b32_e32 v104, v2
	v_mov_b32_e32 v105, v2
	v_mov_b32_e32 v114, v2
	v_mov_b32_e32 v115, v2
	v_mov_b32_e32 v116, v2
	v_mov_b32_e32 v117, v2
	v_mov_b32_e32 v118, v2
	v_mov_b32_e32 v119, v2
	v_mov_b32_e32 v120, v2
	v_mov_b32_e32 v121, v2
	v_mov_b32_e32 v74, v2
	v_mov_b32_e32 v75, v2
	v_mov_b32_e32 v76, v2
	v_mov_b32_e32 v77, v2
	v_mov_b32_e32 v78, v2
	v_mov_b32_e32 v79, v2
	v_mov_b32_e32 v80, v2
	v_mov_b32_e32 v81, v2
	v_mov_b32_e32 v90, v2
	v_mov_b32_e32 v91, v2
	v_mov_b32_e32 v92, v2
	v_mov_b32_e32 v93, v2
	v_mov_b32_e32 v94, v2
	v_mov_b32_e32 v95, v2
	v_mov_b32_e32 v96, v2
	v_mov_b32_e32 v97, v2
	v_mov_b32_e32 v106, v2
	v_mov_b32_e32 v107, v2
	v_mov_b32_e32 v108, v2
	v_mov_b32_e32 v109, v2
	v_mov_b32_e32 v110, v2
	v_mov_b32_e32 v111, v2
	v_mov_b32_e32 v112, v2
	v_mov_b32_e32 v113, v2
	v_mov_b32_e32 v122, v2
	v_mov_b32_e32 v123, v2
	v_mov_b32_e32 v124, v2
	v_mov_b32_e32 v125, v2
	v_mov_b32_e32 v126, v2
	v_mov_b32_e32 v127, v2
	v_mov_b32_e32 v128, v2
	v_mov_b32_e32 v129, v2
	v_add_u32_e32 v249, 0x10000, v164
	ds_read_b128 v[142:145], v249
	ds_read_b128 v[182:185], v249 offset:1024
	ds_read_b128 v[186:189], v249 offset:2048
	ds_read_b128 v[190:193], v249 offset:3072
	ds_read_b128 v[194:197], v166
	ds_read_b128 v[198:201], v166 offset:1024
	ds_read_b128 v[202:205], v166 offset:2048
	ds_read_b128 v[206:209], v166 offset:3072
	ds_read_b128 v[210:213], v166 offset:4096
	ds_read_b128 v[214:217], v166 offset:5120
.LBB0_557:
	s_add_u32 s24, s0, 0xfffc0080
	s_addc_u32 s25, s1, -1
	s_add_i32 s39, 0, 0x10000
	v_add_u32_e32 v162, s39, v164
	s_cmp_eq_u32 s38, 12
	s_cselect_b32 vcc_hi, s77, s25
	s_cselect_b32 vcc_lo, s76, s24
	s_cselect_b32 s49, s45, s50
	s_cselect_b32 s48, s47, s35
	v_lshl_add_u64 v[162:163], s[0:1], 0, v[140:141]
	s_add_i32 m0, s95, 0xc000
	ds_read_b128 v[218:221], v166 offset:6144
	ds_read_b128 v[222:225], v166 offset:7168
	global_load_lds_dwordx4 v[162:163], off
	v_lshl_add_u64 v[250:251], s[0:1], 0, v[138:139]
	s_add_i32 m0, s95, 0xe000
	s_nop 0
	global_load_lds_dwordx4 v[250:251], off
	s_waitcnt lgkmcnt(8)
	s_barrier
	s_waitcnt lgkmcnt(0)
	s_setprio 1
	s_waitcnt lgkmcnt(0)
	v_mfma_f32_16x16x32_bf16 v[126:129], v[142:145], v[194:197], v[126:129]
	v_mfma_f32_16x16x32_bf16 v[126:129], v[182:185], v[198:201], v[126:129]
	v_mfma_f32_16x16x32_bf16 v[122:125], v[186:189], v[194:197], v[122:125]
	v_mfma_f32_16x16x32_bf16 v[122:125], v[190:193], v[198:201], v[122:125]
	v_mfma_f32_16x16x32_bf16 v[110:113], v[142:145], v[202:205], v[110:113]
	v_mfma_f32_16x16x32_bf16 v[110:113], v[182:185], v[206:209], v[110:113]
	v_mfma_f32_16x16x32_bf16 v[106:109], v[186:189], v[202:205], v[106:109]
	v_mfma_f32_16x16x32_bf16 v[106:109], v[190:193], v[206:209], v[106:109]
	v_mfma_f32_16x16x32_bf16 v[94:97], v[142:145], v[210:213], v[94:97]
	v_mfma_f32_16x16x32_bf16 v[94:97], v[182:185], v[214:217], v[94:97]
	v_mfma_f32_16x16x32_bf16 v[90:93], v[186:189], v[210:213], v[90:93]
	v_mfma_f32_16x16x32_bf16 v[90:93], v[190:193], v[214:217], v[90:93]
	v_mfma_f32_16x16x32_bf16 v[78:81], v[142:145], v[218:221], v[78:81]
	v_mfma_f32_16x16x32_bf16 v[78:81], v[182:185], v[222:225], v[78:81]
	v_mfma_f32_16x16x32_bf16 v[74:77], v[186:189], v[218:221], v[74:77]
	s_barrier
; #define PG8_STAGE(bufoff, gbase, voff) do { _Pragma("unroll") for (int _i = 0; _i < 2; ++_i) \
;         __builtin_amdgcn_global_load_lds((const unsigned*)((const char*)(gbase) + (voff)[_i]), (LAS unsigned*)(lds + (bufoff) + ldsw + _i * 8192), 16, 0, 0); } while (0)
; #define PG8_LDA(dst, b, h) do { _Pragma("unroll") for (int m = 0; m < 4; ++m) _Pragma("unroll") for (int k = 0; k < 2; ++k) dst[m][k] = *(const LAS bf16x8*)(lds + PG8_SA(b, h) + aoff + m * 2048 + k * 1024); } while (0)
; #define PG8_LDB(dst, b, h) do { _Pragma("unroll") for (int n = 0; n < 2; ++n) _Pragma("unroll") for (int k = 0; k < 2; ++k) dst[n][k] = *(const LAS bf16x8*)(lds + PG8_SB(b, h) + boff + n * 2048 + k * 1024); } while (0)
; #define PG8_MMA(ai, bj, At, Bt) do { __builtin_amdgcn_s_setprio(1); _Pragma("unroll") for (int m = 0; m < 4; ++m) _Pragma("unroll") for (int n = 0; n < 2; ++n) _Pragma("unroll") for (int k = 0; k < 2; ++k) \
;         acc[ai][bj][m][n] = __builtin_amdgcn_mfma_f32_16x16x32_bf16(Bt[n][k], At[m][k], acc[ai][bj][m][n], 0, 0, 0); __builtin_amdgcn_s_setprio(0); } while (0)
; #define PG8_WAIT_V(n) asm volatile("s_waitcnt vmcnt(" #n ")" ::: "memory")
; #define PG8_WAIT_L(n) asm volatile("s_waitcnt lgkmcnt(" #n ")" ::: "memory")
; #define PG8_BAR __builtin_amdgcn_s_barrier()
; #define PG8_SCHED __builtin_amdgcn_sched_barrier(0)
; template <class Epi, class Sched>
; __device__ __forceinline__ void gemm_phase(LAS unsigned char* lds, const Gemm g, const Sched& S, const Epi& E) {
;     ...
;             PG8_LDB(B1, 0, 1); PG8_STAGE(PG8_SB(0, 0), b2, voffB);
;             PG8_BAR; PG8_WAIT_L(0); PG8_MMA(0, 1, At, B1); PG8_BAR;
;             PG8_LDA(At, 0, 1); PG8_STAGE(PG8_SA(0, 0), a2, voffA);
;             PG8_BAR; PG8_WAIT_L(0); PG8_MMA(1, 0, At, B0); PG8_BAR; PG8_SCHED;
;             PG8_STAGE(PG8_SB(0, 1), b2 + hstep, voffB);
;             PG8_WAIT_V(6); PG8_BAR; PG8_MMA(1, 1, At, B1); PG8_BAR;
;             PG8_LDB(B0, 1, 0); PG8_SCHED; PG8_LDA(At, 1, 0); PG8_STAGE(PG8_SA(0, 1), a2 + hstep, voffA);
	v_mfma_f32_16x16x32_bf16 v[74:77], v[190:193], v[222:225], v[74:77]
	s_setprio 0
	s_add_i32 s51, 0, 0x14000
	v_add_u32_e32 v162, s51, v164
	s_add_i32 s24, s39, s94
	ds_read_b128 v[226:229], v162
	ds_read_b128 v[230:233], v162 offset:1024
	ds_read_b128 v[234:237], v162 offset:2048
	ds_read_b128 v[238:241], v162 offset:3072
	v_lshl_add_u64 v[162:163], s[48:49], 0, v[134:135]
	s_mov_b32 m0, s24
	v_lshl_add_u64 v[168:169], s[48:49], 0, v[130:131]
	global_load_lds_dwordx4 v[162:163], off
	s_add_i32 m0, s24, 0x2000
	s_nop 0
	global_load_lds_dwordx4 v[168:169], off
	s_barrier
	s_waitcnt lgkmcnt(0)
	s_setprio 1
	s_waitcnt lgkmcnt(0)
	v_mfma_f32_16x16x32_bf16 v[118:121], v[226:229], v[194:197], v[118:121]
	v_mfma_f32_16x16x32_bf16 v[118:121], v[230:233], v[198:201], v[118:121]
	v_mfma_f32_16x16x32_bf16 v[114:117], v[234:237], v[194:197], v[114:117]
	v_mfma_f32_16x16x32_bf16 v[114:117], v[238:241], v[198:201], v[114:117]
	v_mfma_f32_16x16x32_bf16 v[102:105], v[226:229], v[202:205], v[102:105]
	v_mfma_f32_16x16x32_bf16 v[102:105], v[230:233], v[206:209], v[102:105]
	v_mfma_f32_16x16x32_bf16 v[98:101], v[234:237], v[202:205], v[98:101]
	v_mfma_f32_16x16x32_bf16 v[98:101], v[238:241], v[206:209], v[98:101]
	v_mfma_f32_16x16x32_bf16 v[86:89], v[226:229], v[210:213], v[86:89]
	v_mfma_f32_16x16x32_bf16 v[86:89], v[230:233], v[214:217], v[86:89]
	v_mfma_f32_16x16x32_bf16 v[82:85], v[234:237], v[210:213], v[82:85]
	v_mfma_f32_16x16x32_bf16 v[82:85], v[238:241], v[214:217], v[82:85]
	v_mfma_f32_16x16x32_bf16 v[70:73], v[226:229], v[218:221], v[70:73]
	v_mfma_f32_16x16x32_bf16 v[70:73], v[230:233], v[222:225], v[70:73]
	v_mfma_f32_16x16x32_bf16 v[66:69], v[234:237], v[218:221], v[66:69]
	s_barrier
	v_mfma_f32_16x16x32_bf16 v[66:69], v[238:241], v[222:225], v[66:69]
	s_setprio 0
	s_mov_b32 m0, s95
	v_lshl_add_u64 v[242:243], vcc, 0, v[136:137]
	ds_read_b128 v[194:197], v166 offset:16384
	ds_read_b128 v[198:201], v166 offset:17408
	ds_read_b128 v[202:205], v166 offset:18432
	ds_read_b128 v[206:209], v166 offset:19456
	ds_read_b128 v[210:213], v166 offset:20480
	ds_read_b128 v[214:217], v166 offset:21504
	ds_read_b128 v[218:221], v166 offset:22528
	ds_read_b128 v[222:225], v166 offset:23552
	global_load_lds_dwordx4 v[242:243], off
	v_lshl_add_u64 v[244:245], vcc, 0, v[132:133]
	s_mov_b32 m0, s96
	s_nop 0
	global_load_lds_dwordx4 v[244:245], off
	s_waitcnt vmcnt(8)
	s_barrier
	s_waitcnt lgkmcnt(0)
	s_setprio 1
	s_waitcnt lgkmcnt(0)
	v_mfma_f32_16x16x32_bf16 v[62:65], v[142:145], v[194:197], v[62:65]
	v_mfma_f32_16x16x32_bf16 v[62:65], v[182:185], v[198:201], v[62:65]
	v_mfma_f32_16x16x32_bf16 v[58:61], v[186:189], v[194:197], v[58:61]
	v_mfma_f32_16x16x32_bf16 v[58:61], v[190:193], v[198:201], v[58:61]
	v_mfma_f32_16x16x32_bf16 v[46:49], v[142:145], v[202:205], v[46:49]
	v_mfma_f32_16x16x32_bf16 v[46:49], v[182:185], v[206:209], v[46:49]
	v_mfma_f32_16x16x32_bf16 v[42:45], v[186:189], v[202:205], v[42:45]
	v_mfma_f32_16x16x32_bf16 v[42:45], v[190:193], v[206:209], v[42:45]
	v_mfma_f32_16x16x32_bf16 v[30:33], v[142:145], v[210:213], v[30:33]
	v_mfma_f32_16x16x32_bf16 v[30:33], v[182:185], v[214:217], v[30:33]
	v_mfma_f32_16x16x32_bf16 v[26:29], v[186:189], v[210:213], v[26:29]
	v_mfma_f32_16x16x32_bf16 v[26:29], v[190:193], v[214:217], v[26:29]
	v_mfma_f32_16x16x32_bf16 v[14:17], v[142:145], v[218:221], v[14:17]
	v_mfma_f32_16x16x32_bf16 v[14:17], v[182:185], v[222:225], v[14:17]
	v_mfma_f32_16x16x32_bf16 v[10:13], v[186:189], v[218:221], v[10:13]
	s_barrier
	v_mfma_f32_16x16x32_bf16 v[10:13], v[190:193], v[222:225], v[10:13]
	s_setprio 0
	s_add_u32 s24, s48, 0x40000
	s_addc_u32 s25, s49, 0
	s_add_i32 s39, s51, s94
	v_lshl_add_u64 v[142:143], s[24:25], 0, v[134:135]
	s_mov_b32 m0, s39
	s_nop 0
	global_load_lds_dwordx4 v[142:143], off
	v_lshl_add_u64 v[250:251], s[24:25], 0, v[130:131]
	s_add_i32 m0, s39, 0x2000
	s_nop 0
	global_load_lds_dwordx4 v[250:251], off
	s_waitcnt vmcnt(6)
	s_barrier
	s_setprio 1
	v_add_u32_e32 v249, 0x18000, v164
	v_mfma_f32_16x16x32_bf16 v[54:57], v[226:229], v[194:197], v[54:57]
	ds_read_b128 v[142:145], v249
	ds_read_b128 v[182:185], v249 offset:1024
	v_mfma_f32_16x16x32_bf16 v[54:57], v[230:233], v[198:201], v[54:57]
	ds_read_b128 v[186:189], v249 offset:2048
	ds_read_b128 v[190:193], v249 offset:3072
	v_mfma_f32_16x16x32_bf16 v[50:53], v[234:237], v[194:197], v[50:53]
	ds_read_b128 v[194:197], v166 offset:32768
	v_mfma_f32_16x16x32_bf16 v[50:53], v[238:241], v[198:201], v[50:53]
	ds_read_b128 v[198:201], v166 offset:33792
	v_mfma_f32_16x16x32_bf16 v[38:41], v[226:229], v[202:205], v[38:41]
	v_mfma_f32_16x16x32_bf16 v[38:41], v[230:233], v[206:209], v[38:41]
	v_mfma_f32_16x16x32_bf16 v[34:37], v[234:237], v[202:205], v[34:37]
	ds_read_b128 v[202:205], v166 offset:34816
	v_mfma_f32_16x16x32_bf16 v[34:37], v[238:241], v[206:209], v[34:37]
	ds_read_b128 v[206:209], v166 offset:35840
	v_mfma_f32_16x16x32_bf16 v[22:25], v[226:229], v[210:213], v[22:25]
	v_mfma_f32_16x16x32_bf16 v[22:25], v[230:233], v[214:217], v[22:25]
	v_mfma_f32_16x16x32_bf16 v[18:21], v[234:237], v[210:213], v[18:21]
	ds_read_b128 v[210:213], v166 offset:36864
	v_mfma_f32_16x16x32_bf16 v[18:21], v[238:241], v[214:217], v[18:21]
	ds_read_b128 v[214:217], v166 offset:37888
	v_mfma_f32_16x16x32_bf16 v[6:9], v[226:229], v[218:221], v[6:9]
	v_mfma_f32_16x16x32_bf16 v[6:9], v[230:233], v[222:225], v[6:9]
	v_mfma_f32_16x16x32_bf16 v[2:5], v[234:237], v[218:221], v[2:5]
	s_barrier
; #define PG8_STAGE(bufoff, gbase, voff) do { _Pragma("unroll") for (int _i = 0; _i < 2; ++_i) \
;         __builtin_amdgcn_global_load_lds((const unsigned*)((const char*)(gbase) + (voff)[_i]), (LAS unsigned*)(lds + (bufoff) + ldsw + _i * 8192), 16, 0, 0); } while (0)
; #define PG8_LDA(dst, b, h) do { _Pragma("unroll") for (int m = 0; m < 4; ++m) _Pragma("unroll") for (int k = 0; k < 2; ++k) dst[m][k] = *(const LAS bf16x8*)(lds + PG8_SA(b, h) + aoff + m * 2048 + k * 1024); } while (0)
; #define PG8_LDB(dst, b, h) do { _Pragma("unroll") for (int n = 0; n < 2; ++n) _Pragma("unroll") for (int k = 0; k < 2; ++k) dst[n][k] = *(const LAS bf16x8*)(lds + PG8_SB(b, h) + boff + n * 2048 + k * 1024); } while (0)
; #define PG8_MMA(ai, bj, At, Bt) do { __builtin_amdgcn_s_setprio(1); _Pragma("unroll") for (int m = 0; m < 4; ++m) _Pragma("unroll") for (int n = 0; n < 2; ++n) _Pragma("unroll") for (int k = 0; k < 2; ++k) \
;         acc[ai][bj][m][n] = __builtin_amdgcn_mfma_f32_16x16x32_bf16(Bt[n][k], At[m][k], acc[ai][bj][m][n], 0, 0, 0); __builtin_amdgcn_s_setprio(0); } while (0)
; #define PG8_WAIT_L(n) asm volatile("s_waitcnt lgkmcnt(" #n ")" ::: "memory")
; #define PG8_BAR __builtin_amdgcn_s_barrier()
; #define PG8_SCHED __builtin_amdgcn_sched_barrier(0)
; template <class Epi, class Sched>
; __device__ __forceinline__ void gemm_phase(LAS unsigned char* lds, const Gemm g, const Sched& S, const Epi& E) {
;     ...
;             PG8_LDB(B0, 1, 0); PG8_SCHED; PG8_LDA(At, 1, 0); PG8_STAGE(PG8_SA(0, 1), a2 + hstep, voffA);
;             PG8_WAIT_L(8); PG8_BAR; PG8_WAIT_L(0); PG8_MMA(0, 0, At, B0); PG8_BAR; PG8_SCHED;
;             PG8_LDB(B1, 1, 1); PG8_STAGE(PG8_SB(1, 0), b3, voffB);
;             PG8_BAR; PG8_WAIT_L(0); PG8_MMA(0, 1, At, B1); PG8_BAR;
	v_mfma_f32_16x16x32_bf16 v[2:5], v[238:241], v[222:225], v[2:5]
	s_setprio 0
	s_add_i32 s39, 0, 0x18000
	v_add_u32_e32 v167, s39, v164
	s_add_u32 s24, vcc_lo, 0x40000
	s_addc_u32 s25, vcc_hi, 0
	s_mov_b32 m0, s97
	v_lshl_add_u64 v[226:227], s[24:25], 0, v[136:137]
	ds_read_b128 v[218:221], v166 offset:38912
	ds_read_b128 v[222:225], v166 offset:39936
	global_load_lds_dwordx4 v[226:227], off
	v_lshl_add_u64 v[250:251], s[24:25], 0, v[132:133]
	s_mov_b32 m0, s98
	s_nop 0
	global_load_lds_dwordx4 v[250:251], off
	s_waitcnt lgkmcnt(8)
	s_barrier
	s_waitcnt lgkmcnt(0)
	s_setprio 1
	s_waitcnt lgkmcnt(0)
	v_mfma_f32_16x16x32_bf16 v[126:129], v[142:145], v[194:197], v[126:129]
	v_mfma_f32_16x16x32_bf16 v[126:129], v[182:185], v[198:201], v[126:129]
	v_mfma_f32_16x16x32_bf16 v[122:125], v[186:189], v[194:197], v[122:125]
	v_mfma_f32_16x16x32_bf16 v[122:125], v[190:193], v[198:201], v[122:125]
	v_mfma_f32_16x16x32_bf16 v[110:113], v[142:145], v[202:205], v[110:113]
	v_mfma_f32_16x16x32_bf16 v[110:113], v[182:185], v[206:209], v[110:113]
	v_mfma_f32_16x16x32_bf16 v[106:109], v[186:189], v[202:205], v[106:109]
	v_mfma_f32_16x16x32_bf16 v[106:109], v[190:193], v[206:209], v[106:109]
	v_mfma_f32_16x16x32_bf16 v[94:97], v[142:145], v[210:213], v[94:97]
	v_mfma_f32_16x16x32_bf16 v[94:97], v[182:185], v[214:217], v[94:97]
	v_mfma_f32_16x16x32_bf16 v[90:93], v[186:189], v[210:213], v[90:93]
	v_mfma_f32_16x16x32_bf16 v[90:93], v[190:193], v[214:217], v[90:93]
	v_mfma_f32_16x16x32_bf16 v[78:81], v[142:145], v[218:221], v[78:81]
	v_mfma_f32_16x16x32_bf16 v[78:81], v[182:185], v[222:225], v[78:81]
	v_mfma_f32_16x16x32_bf16 v[74:77], v[186:189], v[218:221], v[74:77]
	s_barrier
	v_mfma_f32_16x16x32_bf16 v[74:77], v[190:193], v[222:225], v[74:77]
	s_setprio 0
	s_add_i32 s51, 0, 0x1c000
	s_add_i32 s24, s39, s94
	v_add_u32_e32 v167, s51, v164
	v_lshl_add_u64 v[162:163], v[162:163], 0, s[12:13]
	s_mov_b32 m0, s24
	ds_read_b128 v[226:229], v167
	ds_read_b128 v[230:233], v167 offset:1024
	ds_read_b128 v[234:237], v167 offset:2048
	ds_read_b128 v[238:241], v167 offset:3072
	global_load_lds_dwordx4 v[162:163], off
	v_lshl_add_u64 v[250:251], v[168:169], 0, s[12:13]
	s_add_i32 m0, s24, 0x2000
	s_nop 0
	global_load_lds_dwordx4 v[250:251], off
	s_barrier
	s_waitcnt lgkmcnt(0)
	s_setprio 1
	s_waitcnt lgkmcnt(0)
	v_mfma_f32_16x16x32_bf16 v[118:121], v[226:229], v[194:197], v[118:121]
	v_mfma_f32_16x16x32_bf16 v[118:121], v[230:233], v[198:201], v[118:121]
	v_mfma_f32_16x16x32_bf16 v[114:117], v[234:237], v[194:197], v[114:117]
	v_mfma_f32_16x16x32_bf16 v[114:117], v[238:241], v[198:201], v[114:117]
	v_mfma_f32_16x16x32_bf16 v[102:105], v[226:229], v[202:205], v[102:105]
	v_mfma_f32_16x16x32_bf16 v[102:105], v[230:233], v[206:209], v[102:105]
	v_mfma_f32_16x16x32_bf16 v[98:101], v[234:237], v[202:205], v[98:101]
	v_mfma_f32_16x16x32_bf16 v[98:101], v[238:241], v[206:209], v[98:101]
	v_mfma_f32_16x16x32_bf16 v[86:89], v[226:229], v[210:213], v[86:89]
	v_mfma_f32_16x16x32_bf16 v[86:89], v[230:233], v[214:217], v[86:89]
	v_mfma_f32_16x16x32_bf16 v[82:85], v[234:237], v[210:213], v[82:85]
	v_mfma_f32_16x16x32_bf16 v[82:85], v[238:241], v[214:217], v[82:85]
	v_mfma_f32_16x16x32_bf16 v[70:73], v[226:229], v[218:221], v[70:73]
	v_mfma_f32_16x16x32_bf16 v[70:73], v[230:233], v[222:225], v[70:73]
	v_mfma_f32_16x16x32_bf16 v[66:69], v[234:237], v[218:221], v[66:69]
	s_barrier
; #define PG8_STAGE(bufoff, gbase, voff) do { _Pragma("unroll") for (int _i = 0; _i < 2; ++_i) \
;         __builtin_amdgcn_global_load_lds((const unsigned*)((const char*)(gbase) + (voff)[_i]), (LAS unsigned*)(lds + (bufoff) + ldsw + _i * 8192), 16, 0, 0); } while (0)
; #define PG8_LDA(dst, b, h) do { _Pragma("unroll") for (int m = 0; m < 4; ++m) _Pragma("unroll") for (int k = 0; k < 2; ++k) dst[m][k] = *(const LAS bf16x8*)(lds + PG8_SA(b, h) + aoff + m * 2048 + k * 1024); } while (0)
; #define PG8_MMA(ai, bj, At, Bt) do { __builtin_amdgcn_s_setprio(1); _Pragma("unroll") for (int m = 0; m < 4; ++m) _Pragma("unroll") for (int n = 0; n < 2; ++n) _Pragma("unroll") for (int k = 0; k < 2; ++k) \
;         acc[ai][bj][m][n] = __builtin_amdgcn_mfma_f32_16x16x32_bf16(Bt[n][k], At[m][k], acc[ai][bj][m][n], 0, 0, 0); __builtin_amdgcn_s_setprio(0); } while (0)
; #define PG8_WAIT_V(n) asm volatile("s_waitcnt vmcnt(" #n ")" ::: "memory")
; #define PG8_WAIT_L(n) asm volatile("s_waitcnt lgkmcnt(" #n ")" ::: "memory")
; #define PG8_BAR __builtin_amdgcn_s_barrier()
; #define PG8_SCHED __builtin_amdgcn_sched_barrier(0)
; template <class Epi, class Sched>
; __device__ __forceinline__ void gemm_phase(LAS unsigned char* lds, const Gemm g, const Sched& S, const Epi& E) {
;     ...
;             PG8_LDA(At, 1, 1); PG8_STAGE(PG8_SA(1, 0), a3, voffA);
;             PG8_BAR; PG8_WAIT_L(0); PG8_MMA(1, 0, At, B0); PG8_BAR; PG8_SCHED;
;             PG8_STAGE(PG8_SB(1, 1), b3 + hstep, voffB);
;             PG8_WAIT_V(6); PG8_BAR; PG8_MMA(1, 1, At, B1); PG8_BAR;
;         }
;         if (wr == 0) PG8_BAR;
	v_mfma_f32_16x16x32_bf16 v[66:69], v[238:241], v[222:225], v[66:69]
	s_setprio 0
	s_mov_b32 m0, s99
	v_lshl_add_u64 v[162:163], v[242:243], 0, s[12:13]
	ds_read_b128 v[194:197], v166 offset:49152
	ds_read_b128 v[198:201], v166 offset:50176
	ds_read_b128 v[202:205], v166 offset:51200
	ds_read_b128 v[206:209], v166 offset:52224
	ds_read_b128 v[210:213], v166 offset:53248
	ds_read_b128 v[214:217], v166 offset:54272
	ds_read_b128 v[218:221], v166 offset:55296
	ds_read_b128 v[222:225], v166 offset:56320
	global_load_lds_dwordx4 v[162:163], off
	v_lshl_add_u64 v[250:251], v[244:245], 0, s[12:13]
	s_mov_b32 m0, s82
	s_nop 0
	global_load_lds_dwordx4 v[250:251], off
	s_waitcnt vmcnt(8)
	s_barrier
	s_waitcnt lgkmcnt(0)
	s_setprio 1
	s_waitcnt lgkmcnt(0)
	v_mfma_f32_16x16x32_bf16 v[62:65], v[142:145], v[194:197], v[62:65]
	v_mfma_f32_16x16x32_bf16 v[62:65], v[182:185], v[198:201], v[62:65]
	v_mfma_f32_16x16x32_bf16 v[58:61], v[186:189], v[194:197], v[58:61]
	v_mfma_f32_16x16x32_bf16 v[58:61], v[190:193], v[198:201], v[58:61]
	v_mfma_f32_16x16x32_bf16 v[46:49], v[142:145], v[202:205], v[46:49]
	v_mfma_f32_16x16x32_bf16 v[46:49], v[182:185], v[206:209], v[46:49]
	v_mfma_f32_16x16x32_bf16 v[42:45], v[186:189], v[202:205], v[42:45]
	v_mfma_f32_16x16x32_bf16 v[42:45], v[190:193], v[206:209], v[42:45]
	v_mfma_f32_16x16x32_bf16 v[30:33], v[142:145], v[210:213], v[30:33]
	v_mfma_f32_16x16x32_bf16 v[30:33], v[182:185], v[214:217], v[30:33]
	v_mfma_f32_16x16x32_bf16 v[26:29], v[186:189], v[210:213], v[26:29]
	v_mfma_f32_16x16x32_bf16 v[26:29], v[190:193], v[214:217], v[26:29]
	v_mfma_f32_16x16x32_bf16 v[14:17], v[142:145], v[218:221], v[14:17]
	v_mfma_f32_16x16x32_bf16 v[14:17], v[182:185], v[222:225], v[14:17]
	v_mfma_f32_16x16x32_bf16 v[10:13], v[186:189], v[218:221], v[10:13]
	s_barrier
	v_mfma_f32_16x16x32_bf16 v[10:13], v[190:193], v[222:225], v[10:13]
	s_setprio 0
	s_add_u32 s24, s48, 0x40080
	s_addc_u32 s25, s49, 0
	s_add_i32 s39, s51, s94
	v_lshl_add_u64 v[142:143], s[24:25], 0, v[134:135]
	s_mov_b32 m0, s39
	s_nop 0
	global_load_lds_dwordx4 v[142:143], off
	v_lshl_add_u64 v[250:251], s[24:25], 0, v[130:131]
	s_add_i32 m0, s39, 0x2000
	s_nop 0
	global_load_lds_dwordx4 v[250:251], off
	s_waitcnt vmcnt(6)
	s_barrier
	s_setprio 1
	v_add_u32_e32 v249, 0x10000, v164
	v_mfma_f32_16x16x32_bf16 v[54:57], v[226:229], v[194:197], v[54:57]
	ds_read_b128 v[142:145], v249
	ds_read_b128 v[182:185], v249 offset:1024
	v_mfma_f32_16x16x32_bf16 v[54:57], v[230:233], v[198:201], v[54:57]
	ds_read_b128 v[186:189], v249 offset:2048
	ds_read_b128 v[190:193], v249 offset:3072
	v_mfma_f32_16x16x32_bf16 v[50:53], v[234:237], v[194:197], v[50:53]
	ds_read_b128 v[194:197], v166
	v_mfma_f32_16x16x32_bf16 v[50:53], v[238:241], v[198:201], v[50:53]
	ds_read_b128 v[198:201], v166 offset:1024
	v_mfma_f32_16x16x32_bf16 v[38:41], v[226:229], v[202:205], v[38:41]
	v_mfma_f32_16x16x32_bf16 v[38:41], v[230:233], v[206:209], v[38:41]
	v_mfma_f32_16x16x32_bf16 v[34:37], v[234:237], v[202:205], v[34:37]
	ds_read_b128 v[202:205], v166 offset:2048
	v_mfma_f32_16x16x32_bf16 v[34:37], v[238:241], v[206:209], v[34:37]
	ds_read_b128 v[206:209], v166 offset:3072
	v_mfma_f32_16x16x32_bf16 v[22:25], v[226:229], v[210:213], v[22:25]
	v_mfma_f32_16x16x32_bf16 v[22:25], v[230:233], v[214:217], v[22:25]
	v_mfma_f32_16x16x32_bf16 v[18:21], v[234:237], v[210:213], v[18:21]
	ds_read_b128 v[210:213], v166 offset:4096
	v_mfma_f32_16x16x32_bf16 v[18:21], v[238:241], v[214:217], v[18:21]
	ds_read_b128 v[214:217], v166 offset:5120
	v_mfma_f32_16x16x32_bf16 v[6:9], v[226:229], v[218:221], v[6:9]
	v_mfma_f32_16x16x32_bf16 v[6:9], v[230:233], v[222:225], v[6:9]
	v_mfma_f32_16x16x32_bf16 v[2:5], v[234:237], v[218:221], v[2:5]
	s_barrier
	v_mfma_f32_16x16x32_bf16 v[2:5], v[238:241], v[222:225], v[2:5]
	s_setprio 0
	s_add_i32 s38, s38, 2
	s_add_u32 s35, s35, 0x100
	s_addc_u32 s50, s50, 0
	s_add_u32 s0, s0, 0x100
	s_addc_u32 s1, s1, 0
	s_cmp_gt_u32 s38, 13
	s_cbranch_scc0 .LBB0_557
	s_waitcnt lgkmcnt(0)
	s_and_b64 vcc, exec, s[42:43]
	s_cbranch_vccz .LBB0_560
	s_barrier

; #define PG8_STAGE(bufoff, gbase, voff) do { _Pragma("unroll") for (int _i = 0; _i < 2; ++_i) \
;         __builtin_amdgcn_global_load_lds((const unsigned*)((const char*)(gbase) + (voff)[_i]), (LAS unsigned*)(lds + (bufoff) + ldsw + _i * 8192), 16, 0, 0); } while (0)
; #define PG8_LDA(dst, b, h) do { _Pragma("unroll") for (int m = 0; m < 4; ++m) _Pragma("unroll") for (int k = 0; k < 2; ++k) dst[m][k] = *(const LAS bf16x8*)(lds + PG8_SA(b, h) + aoff + m * 2048 + k * 1024); } while (0)
; #define PG8_LDB(dst, b, h) do { _Pragma("unroll") for (int n = 0; n < 2; ++n) _Pragma("unroll") for (int k = 0; k < 2; ++k) dst[n][k] = *(const LAS bf16x8*)(lds + PG8_SB(b, h) + boff + n * 2048 + k * 1024); } while (0)
; #define PG8_MMA(ai, bj, At, Bt) do { __builtin_amdgcn_s_setprio(1); _Pragma("unroll") for (int m = 0; m < 4; ++m) _Pragma("unroll") for (int n = 0; n < 2; ++n) _Pragma("unroll") for (int k = 0; k < 2; ++k) \
;         acc[ai][bj][m][n] = __builtin_amdgcn_mfma_f32_16x16x32_bf16(Bt[n][k], At[m][k], acc[ai][bj][m][n], 0, 0, 0); __builtin_amdgcn_s_setprio(0); } while (0)
; #define PG8_BAR __builtin_amdgcn_s_barrier()
; template <class Epi, class Sched>
; __device__ __forceinline__ void gemm_phase(LAS unsigned char* lds, const Gemm g, const Sched& S, const Epi& E) {
;     ...
;         const bool has_next = S.next(ui + 1, nxt);
;         const char* nA = has_next ? PG8_APANEL(nxt.pm) : cA; const char* nB = has_next ? (const char*)g.Bt + (size_t)nxt.pn * tstep : cB;
;         for (int t = 0; t < nt; t += 2) {
;             const bool last = (t == nt - 2);
;             const char* a1 = cA + (size_t)(t + 1) * kstep;
;             const char* a2 = last ? nA : cA + (size_t)(t + 2) * kstep; const char* b2 = last ? nB : cB + (size_t)(t + 2) * kstep;
;             const char* a3 = a2 + kstep; const char* b3 = b2 + kstep;
;             PG8_LDB(B0, 0, 0); PG8_SCHED; PG8_LDA(At, 0, 0); PG8_STAGE(PG8_SA(1, 1), a1 + hstep, voffA);
;             PG8_WAIT_L(8); PG8_BAR; PG8_WAIT_L(0); PG8_MMA(0, 0, At, B0); PG8_BAR; PG8_SCHED;
;     ...
; #pragma unroll
;         for (int a = 0; a < 2; ++a)
; #pragma unroll
;             for (int b = 0; b < 2; ++b)
; #pragma unroll
;                 for (int m = 0; m < 4; ++m)
; #pragma unroll
;                     for (int n = 0; n < 2; ++n) acc[a][b][m][n] = (f32x4){0.f, 0.f, 0.f, 0.f};
;         cur = nxt; cA = nA; cB = nB; ++ui;
.LBB0_626:
	s_ashr_i32 s43, s42, 31
	s_lshl_b64 s[24:25], s[42:43], 21
	s_add_u32 s60, s55, s24
	s_addc_u32 s61, s82, s25
	s_and_b64 s[0:1], s[0:1], exec
	s_cselect_b32 s43, s61, s49
	s_cselect_b32 s45, s60, s48
	s_add_u32 s35, s48, 0x100
	s_addc_u32 s50, s49, 0
	s_add_u32 s0, s76, 0x100080
	v_mov_b32_e32 v2, 0
	s_addc_u32 s1, s77, 0
	s_mov_b32 s98, -2
	v_mov_b32_e32 v3, v2
	v_mov_b32_e32 v4, v2
	v_mov_b32_e32 v5, v2
	v_mov_b32_e32 v6, v2
	v_mov_b32_e32 v7, v2
	v_mov_b32_e32 v8, v2
	v_mov_b32_e32 v9, v2
	v_mov_b32_e32 v10, v2
	v_mov_b32_e32 v11, v2
	v_mov_b32_e32 v12, v2
	v_mov_b32_e32 v13, v2
	v_mov_b32_e32 v18, v2
	v_mov_b32_e32 v19, v2
	v_mov_b32_e32 v20, v2
	v_mov_b32_e32 v21, v2
	v_mov_b32_e32 v26, v2
	v_mov_b32_e32 v27, v2
	v_mov_b32_e32 v28, v2
	v_mov_b32_e32 v29, v2
	v_mov_b32_e32 v34, v2
	v_mov_b32_e32 v35, v2
	v_mov_b32_e32 v36, v2
	v_mov_b32_e32 v37, v2
	v_mov_b32_e32 v42, v2
	v_mov_b32_e32 v43, v2
	v_mov_b32_e32 v44, v2
	v_mov_b32_e32 v45, v2
	v_mov_b32_e32 v50, v2
	v_mov_b32_e32 v51, v2
	v_mov_b32_e32 v52, v2
	v_mov_b32_e32 v53, v2
	v_mov_b32_e32 v14, v2
	v_mov_b32_e32 v15, v2
	v_mov_b32_e32 v16, v2
	v_mov_b32_e32 v17, v2
	v_mov_b32_e32 v22, v2
	v_mov_b32_e32 v23, v2
	v_mov_b32_e32 v24, v2
	v_mov_b32_e32 v25, v2
	v_mov_b32_e32 v30, v2
	v_mov_b32_e32 v31, v2
	v_mov_b32_e32 v32, v2
	v_mov_b32_e32 v33, v2
	v_mov_b32_e32 v38, v2
	v_mov_b32_e32 v39, v2
	v_mov_b32_e32 v40, v2
	v_mov_b32_e32 v41, v2
	v_mov_b32_e32 v46, v2
	v_mov_b32_e32 v47, v2
	v_mov_b32_e32 v48, v2
	v_mov_b32_e32 v49, v2
	v_mov_b32_e32 v54, v2
	v_mov_b32_e32 v55, v2
	v_mov_b32_e32 v56, v2
	v_mov_b32_e32 v57, v2
	v_mov_b32_e32 v58, v2
	v_mov_b32_e32 v59, v2
	v_mov_b32_e32 v60, v2
	v_mov_b32_e32 v61, v2
	v_mov_b32_e32 v62, v2
	v_mov_b32_e32 v63, v2
	v_mov_b32_e32 v64, v2
	v_mov_b32_e32 v65, v2
	v_mov_b32_e32 v66, v2
	v_mov_b32_e32 v67, v2
	v_mov_b32_e32 v68, v2
	v_mov_b32_e32 v69, v2
	v_mov_b32_e32 v70, v2
	v_mov_b32_e32 v71, v2
	v_mov_b32_e32 v72, v2
	v_mov_b32_e32 v73, v2
	v_mov_b32_e32 v74, v2
	v_mov_b32_e32 v75, v2
	v_mov_b32_e32 v76, v2
	v_mov_b32_e32 v77, v2
	v_mov_b32_e32 v82, v2
	v_mov_b32_e32 v83, v2
	v_mov_b32_e32 v84, v2
	v_mov_b32_e32 v85, v2
	v_mov_b32_e32 v90, v2
	v_mov_b32_e32 v91, v2
	v_mov_b32_e32 v92, v2
	v_mov_b32_e32 v93, v2
	v_mov_b32_e32 v98, v2
	v_mov_b32_e32 v99, v2
	v_mov_b32_e32 v100, v2
	v_mov_b32_e32 v101, v2
	v_mov_b32_e32 v106, v2
	v_mov_b32_e32 v107, v2
	v_mov_b32_e32 v108, v2
	v_mov_b32_e32 v109, v2
	v_mov_b32_e32 v114, v2
	v_mov_b32_e32 v115, v2
	v_mov_b32_e32 v116, v2
	v_mov_b32_e32 v117, v2
	v_mov_b32_e32 v78, v2
	v_mov_b32_e32 v79, v2
	v_mov_b32_e32 v80, v2
	v_mov_b32_e32 v81, v2
	v_mov_b32_e32 v86, v2
	v_mov_b32_e32 v87, v2
	v_mov_b32_e32 v88, v2
	v_mov_b32_e32 v89, v2
	v_mov_b32_e32 v94, v2
	v_mov_b32_e32 v95, v2
	v_mov_b32_e32 v96, v2
	v_mov_b32_e32 v97, v2
	v_mov_b32_e32 v102, v2
	v_mov_b32_e32 v103, v2
	v_mov_b32_e32 v104, v2
	v_mov_b32_e32 v105, v2
	v_mov_b32_e32 v110, v2
	v_mov_b32_e32 v111, v2
	v_mov_b32_e32 v112, v2
	v_mov_b32_e32 v113, v2
	v_mov_b32_e32 v118, v2
	v_mov_b32_e32 v119, v2
	v_mov_b32_e32 v120, v2
	v_mov_b32_e32 v121, v2
	v_mov_b32_e32 v122, v2
	v_mov_b32_e32 v123, v2
	v_mov_b32_e32 v124, v2
	v_mov_b32_e32 v125, v2
	v_mov_b32_e32 v126, v2
	v_mov_b32_e32 v127, v2
	v_mov_b32_e32 v128, v2
	v_mov_b32_e32 v129, v2
	v_add_u32_e32 v249, 0x10000, v144
	ds_read_b128 v[164:167], v249
	ds_read_b128 v[182:185], v249 offset:1024
	ds_read_b128 v[186:189], v249 offset:2048
	ds_read_b128 v[190:193], v249 offset:3072
	ds_read_b128 v[194:197], v162
	ds_read_b128 v[198:201], v162 offset:1024
	ds_read_b128 v[202:205], v162 offset:2048
	ds_read_b128 v[206:209], v162 offset:3072
	ds_read_b128 v[210:213], v162 offset:4096
	ds_read_b128 v[214:217], v162 offset:5120
.LBB0_627:
	s_add_u32 s24, s0, 0xfff00080
	s_addc_u32 s25, s1, -1
	s_add_i32 s51, 0, 0x10000
	v_add_u32_e32 v142, s51, v144
	s_cmp_eq_u32 s98, 60
	s_cselect_b32 s77, s47, s25
	s_cselect_b32 s76, s46, s24
	s_cselect_b32 s49, s43, s50
	s_cselect_b32 s48, s45, s35
	v_lshl_add_u64 v[142:143], s[0:1], 0, v[140:141]
	s_add_i32 m0, s86, 0xc000
	ds_read_b128 v[218:221], v162 offset:6144
	ds_read_b128 v[222:225], v162 offset:7168
	global_load_lds_dwordx4 v[142:143], off
	v_lshl_add_u64 v[250:251], s[0:1], 0, v[138:139]
	s_add_i32 m0, s86, 0xe000
	s_nop 0
	global_load_lds_dwordx4 v[250:251], off
	s_waitcnt lgkmcnt(8)
	s_barrier
	s_waitcnt lgkmcnt(0)
	s_setprio 1
	s_waitcnt lgkmcnt(0)
	v_mfma_f32_16x16x32_bf16 v[126:129], v[164:167], v[194:197], v[126:129]
	v_mfma_f32_16x16x32_bf16 v[126:129], v[182:185], v[198:201], v[126:129]
	v_mfma_f32_16x16x32_bf16 v[122:125], v[186:189], v[194:197], v[122:125]
	v_mfma_f32_16x16x32_bf16 v[122:125], v[190:193], v[198:201], v[122:125]
	v_mfma_f32_16x16x32_bf16 v[118:121], v[164:167], v[202:205], v[118:121]
	v_mfma_f32_16x16x32_bf16 v[118:121], v[182:185], v[206:209], v[118:121]
	v_mfma_f32_16x16x32_bf16 v[110:113], v[186:189], v[202:205], v[110:113]
	v_mfma_f32_16x16x32_bf16 v[110:113], v[190:193], v[206:209], v[110:113]
	v_mfma_f32_16x16x32_bf16 v[102:105], v[164:167], v[210:213], v[102:105]
	v_mfma_f32_16x16x32_bf16 v[102:105], v[182:185], v[214:217], v[102:105]
	v_mfma_f32_16x16x32_bf16 v[94:97], v[186:189], v[210:213], v[94:97]
	v_mfma_f32_16x16x32_bf16 v[94:97], v[190:193], v[214:217], v[94:97]
	v_mfma_f32_16x16x32_bf16 v[86:89], v[164:167], v[218:221], v[86:89]
	v_mfma_f32_16x16x32_bf16 v[86:89], v[182:185], v[222:225], v[86:89]
	v_mfma_f32_16x16x32_bf16 v[78:81], v[186:189], v[218:221], v[78:81]
	s_barrier
; #define PG8_STAGE(bufoff, gbase, voff) do { _Pragma("unroll") for (int _i = 0; _i < 2; ++_i) \
;         __builtin_amdgcn_global_load_lds((const unsigned*)((const char*)(gbase) + (voff)[_i]), (LAS unsigned*)(lds + (bufoff) + ldsw + _i * 8192), 16, 0, 0); } while (0)
; #define PG8_LDA(dst, b, h) do { _Pragma("unroll") for (int m = 0; m < 4; ++m) _Pragma("unroll") for (int k = 0; k < 2; ++k) dst[m][k] = *(const LAS bf16x8*)(lds + PG8_SA(b, h) + aoff + m * 2048 + k * 1024); } while (0)
; #define PG8_LDB(dst, b, h) do { _Pragma("unroll") for (int n = 0; n < 2; ++n) _Pragma("unroll") for (int k = 0; k < 2; ++k) dst[n][k] = *(const LAS bf16x8*)(lds + PG8_SB(b, h) + boff + n * 2048 + k * 1024); } while (0)
; #define PG8_MMA(ai, bj, At, Bt) do { __builtin_amdgcn_s_setprio(1); _Pragma("unroll") for (int m = 0; m < 4; ++m) _Pragma("unroll") for (int n = 0; n < 2; ++n) _Pragma("unroll") for (int k = 0; k < 2; ++k) \
;         acc[ai][bj][m][n] = __builtin_amdgcn_mfma_f32_16x16x32_bf16(Bt[n][k], At[m][k], acc[ai][bj][m][n], 0, 0, 0); __builtin_amdgcn_s_setprio(0); } while (0)
; #define PG8_WAIT_V(n) asm volatile("s_waitcnt vmcnt(" #n ")" ::: "memory")
; #define PG8_WAIT_L(n) asm volatile("s_waitcnt lgkmcnt(" #n ")" ::: "memory")
; #define PG8_BAR __builtin_amdgcn_s_barrier()
; #define PG8_SCHED __builtin_amdgcn_sched_barrier(0)
; template <class Epi, class Sched>
; __device__ __forceinline__ void gemm_phase(LAS unsigned char* lds, const Gemm g, const Sched& S, const Epi& E) {
;     ...
;             PG8_LDB(B1, 0, 1); PG8_STAGE(PG8_SB(0, 0), b2, voffB);
;             PG8_BAR; PG8_WAIT_L(0); PG8_MMA(0, 1, At, B1); PG8_BAR;
;             PG8_LDA(At, 0, 1); PG8_STAGE(PG8_SA(0, 0), a2, voffA);
;             PG8_BAR; PG8_WAIT_L(0); PG8_MMA(1, 0, At, B0); PG8_BAR; PG8_SCHED;
;             PG8_STAGE(PG8_SB(0, 1), b2 + hstep, voffB);
;             PG8_WAIT_V(6); PG8_BAR; PG8_MMA(1, 1, At, B1); PG8_BAR;
;             PG8_LDB(B0, 1, 0); PG8_SCHED; PG8_LDA(At, 1, 0); PG8_STAGE(PG8_SA(0, 1), a2 + hstep, voffA);
	v_mfma_f32_16x16x32_bf16 v[78:81], v[190:193], v[222:225], v[78:81]
	s_setprio 0
	s_add_i32 s99, 0, 0x14000
	v_add_u32_e32 v142, s99, v144
	s_add_i32 s24, s51, s83
	ds_read_b128 v[226:229], v142
	ds_read_b128 v[230:233], v142 offset:1024
	ds_read_b128 v[234:237], v142 offset:2048
	ds_read_b128 v[238:241], v142 offset:3072
	v_lshl_add_u64 v[142:143], s[48:49], 0, v[134:135]
	s_mov_b32 m0, s24
	v_lshl_add_u64 v[168:169], s[48:49], 0, v[130:131]
	global_load_lds_dwordx4 v[142:143], off
	s_add_i32 m0, s24, 0x2000
	s_nop 0
	global_load_lds_dwordx4 v[168:169], off
	s_barrier
	s_waitcnt lgkmcnt(0)
	s_setprio 1
	s_waitcnt lgkmcnt(0)
	v_mfma_f32_16x16x32_bf16 v[114:117], v[226:229], v[194:197], v[114:117]
	v_mfma_f32_16x16x32_bf16 v[114:117], v[230:233], v[198:201], v[114:117]
	v_mfma_f32_16x16x32_bf16 v[106:109], v[234:237], v[194:197], v[106:109]
	v_mfma_f32_16x16x32_bf16 v[106:109], v[238:241], v[198:201], v[106:109]
	v_mfma_f32_16x16x32_bf16 v[98:101], v[226:229], v[202:205], v[98:101]
	v_mfma_f32_16x16x32_bf16 v[98:101], v[230:233], v[206:209], v[98:101]
	v_mfma_f32_16x16x32_bf16 v[90:93], v[234:237], v[202:205], v[90:93]
	v_mfma_f32_16x16x32_bf16 v[90:93], v[238:241], v[206:209], v[90:93]
	v_mfma_f32_16x16x32_bf16 v[82:85], v[226:229], v[210:213], v[82:85]
	v_mfma_f32_16x16x32_bf16 v[82:85], v[230:233], v[214:217], v[82:85]
	v_mfma_f32_16x16x32_bf16 v[74:77], v[234:237], v[210:213], v[74:77]
	v_mfma_f32_16x16x32_bf16 v[74:77], v[238:241], v[214:217], v[74:77]
	v_mfma_f32_16x16x32_bf16 v[70:73], v[226:229], v[218:221], v[70:73]
	v_mfma_f32_16x16x32_bf16 v[70:73], v[230:233], v[222:225], v[70:73]
	v_mfma_f32_16x16x32_bf16 v[66:69], v[234:237], v[218:221], v[66:69]
	s_barrier
	v_mfma_f32_16x16x32_bf16 v[66:69], v[238:241], v[222:225], v[66:69]
	s_setprio 0
	s_mov_b32 m0, s86
	v_lshl_add_u64 v[242:243], s[76:77], 0, v[136:137]
	ds_read_b128 v[194:197], v162 offset:16384
	ds_read_b128 v[198:201], v162 offset:17408
	ds_read_b128 v[202:205], v162 offset:18432
	ds_read_b128 v[206:209], v162 offset:19456
	ds_read_b128 v[210:213], v162 offset:20480
	ds_read_b128 v[214:217], v162 offset:21504
	ds_read_b128 v[218:221], v162 offset:22528
	ds_read_b128 v[222:225], v162 offset:23552
	global_load_lds_dwordx4 v[242:243], off
	v_lshl_add_u64 v[244:245], s[76:77], 0, v[132:133]
	s_mov_b32 m0, s92
	s_nop 0
	global_load_lds_dwordx4 v[244:245], off
	s_waitcnt vmcnt(8)
	s_barrier
	s_waitcnt lgkmcnt(0)
	s_setprio 1
	s_waitcnt lgkmcnt(0)
	v_mfma_f32_16x16x32_bf16 v[62:65], v[164:167], v[194:197], v[62:65]
	v_mfma_f32_16x16x32_bf16 v[62:65], v[182:185], v[198:201], v[62:65]
	v_mfma_f32_16x16x32_bf16 v[58:61], v[186:189], v[194:197], v[58:61]
	v_mfma_f32_16x16x32_bf16 v[58:61], v[190:193], v[198:201], v[58:61]
	v_mfma_f32_16x16x32_bf16 v[54:57], v[164:167], v[202:205], v[54:57]
	v_mfma_f32_16x16x32_bf16 v[54:57], v[182:185], v[206:209], v[54:57]
	v_mfma_f32_16x16x32_bf16 v[46:49], v[186:189], v[202:205], v[46:49]
	v_mfma_f32_16x16x32_bf16 v[46:49], v[190:193], v[206:209], v[46:49]
	v_mfma_f32_16x16x32_bf16 v[38:41], v[164:167], v[210:213], v[38:41]
	v_mfma_f32_16x16x32_bf16 v[38:41], v[182:185], v[214:217], v[38:41]
	v_mfma_f32_16x16x32_bf16 v[30:33], v[186:189], v[210:213], v[30:33]
	v_mfma_f32_16x16x32_bf16 v[30:33], v[190:193], v[214:217], v[30:33]
	v_mfma_f32_16x16x32_bf16 v[22:25], v[164:167], v[218:221], v[22:25]
	v_mfma_f32_16x16x32_bf16 v[22:25], v[182:185], v[222:225], v[22:25]
	v_mfma_f32_16x16x32_bf16 v[14:17], v[186:189], v[218:221], v[14:17]
	s_barrier
	v_mfma_f32_16x16x32_bf16 v[14:17], v[190:193], v[222:225], v[14:17]
	s_setprio 0
	s_add_u32 s24, s48, 0x100000
	s_addc_u32 s25, s49, 0
	s_add_i32 s51, s99, s83
	v_lshl_add_u64 v[164:165], s[24:25], 0, v[134:135]
	s_mov_b32 m0, s51
	s_nop 0
	global_load_lds_dwordx4 v[164:165], off
	v_lshl_add_u64 v[250:251], s[24:25], 0, v[130:131]
	s_add_i32 m0, s51, 0x2000
	s_nop 0
	global_load_lds_dwordx4 v[250:251], off
	s_waitcnt vmcnt(6)
	s_barrier
	s_setprio 1
	v_add_u32_e32 v249, 0x18000, v144
	v_mfma_f32_16x16x32_bf16 v[50:53], v[226:229], v[194:197], v[50:53]
	ds_read_b128 v[164:167], v249
	ds_read_b128 v[182:185], v249 offset:1024
	v_mfma_f32_16x16x32_bf16 v[50:53], v[230:233], v[198:201], v[50:53]
	ds_read_b128 v[186:189], v249 offset:2048
	ds_read_b128 v[190:193], v249 offset:3072
	v_mfma_f32_16x16x32_bf16 v[42:45], v[234:237], v[194:197], v[42:45]
	ds_read_b128 v[194:197], v162 offset:32768
	v_mfma_f32_16x16x32_bf16 v[42:45], v[238:241], v[198:201], v[42:45]
	ds_read_b128 v[198:201], v162 offset:33792
	v_mfma_f32_16x16x32_bf16 v[34:37], v[226:229], v[202:205], v[34:37]
	v_mfma_f32_16x16x32_bf16 v[34:37], v[230:233], v[206:209], v[34:37]
	v_mfma_f32_16x16x32_bf16 v[26:29], v[234:237], v[202:205], v[26:29]
	ds_read_b128 v[202:205], v162 offset:34816
	v_mfma_f32_16x16x32_bf16 v[26:29], v[238:241], v[206:209], v[26:29]
	ds_read_b128 v[206:209], v162 offset:35840
	v_mfma_f32_16x16x32_bf16 v[18:21], v[226:229], v[210:213], v[18:21]
	v_mfma_f32_16x16x32_bf16 v[18:21], v[230:233], v[214:217], v[18:21]
	v_mfma_f32_16x16x32_bf16 v[10:13], v[234:237], v[210:213], v[10:13]
	ds_read_b128 v[210:213], v162 offset:36864
	v_mfma_f32_16x16x32_bf16 v[10:13], v[238:241], v[214:217], v[10:13]
	ds_read_b128 v[214:217], v162 offset:37888
	v_mfma_f32_16x16x32_bf16 v[6:9], v[226:229], v[218:221], v[6:9]
	v_mfma_f32_16x16x32_bf16 v[6:9], v[230:233], v[222:225], v[6:9]
	v_mfma_f32_16x16x32_bf16 v[2:5], v[234:237], v[218:221], v[2:5]
	s_barrier
; #define PG8_STAGE(bufoff, gbase, voff) do { _Pragma("unroll") for (int _i = 0; _i < 2; ++_i) \
;         __builtin_amdgcn_global_load_lds((const unsigned*)((const char*)(gbase) + (voff)[_i]), (LAS unsigned*)(lds + (bufoff) + ldsw + _i * 8192), 16, 0, 0); } while (0)
; #define PG8_LDA(dst, b, h) do { _Pragma("unroll") for (int m = 0; m < 4; ++m) _Pragma("unroll") for (int k = 0; k < 2; ++k) dst[m][k] = *(const LAS bf16x8*)(lds + PG8_SA(b, h) + aoff + m * 2048 + k * 1024); } while (0)
; #define PG8_LDB(dst, b, h) do { _Pragma("unroll") for (int n = 0; n < 2; ++n) _Pragma("unroll") for (int k = 0; k < 2; ++k) dst[n][k] = *(const LAS bf16x8*)(lds + PG8_SB(b, h) + boff + n * 2048 + k * 1024); } while (0)
; #define PG8_MMA(ai, bj, At, Bt) do { __builtin_amdgcn_s_setprio(1); _Pragma("unroll") for (int m = 0; m < 4; ++m) _Pragma("unroll") for (int n = 0; n < 2; ++n) _Pragma("unroll") for (int k = 0; k < 2; ++k) \
;         acc[ai][bj][m][n] = __builtin_amdgcn_mfma_f32_16x16x32_bf16(Bt[n][k], At[m][k], acc[ai][bj][m][n], 0, 0, 0); __builtin_amdgcn_s_setprio(0); } while (0)
; #define PG8_WAIT_L(n) asm volatile("s_waitcnt lgkmcnt(" #n ")" ::: "memory")
; #define PG8_BAR __builtin_amdgcn_s_barrier()
; #define PG8_SCHED __builtin_amdgcn_sched_barrier(0)
; template <class Epi, class Sched>
; __device__ __forceinline__ void gemm_phase(LAS unsigned char* lds, const Gemm g, const Sched& S, const Epi& E) {
;     ...
;             PG8_LDB(B0, 1, 0); PG8_SCHED; PG8_LDA(At, 1, 0); PG8_STAGE(PG8_SA(0, 1), a2 + hstep, voffA);
;             PG8_WAIT_L(8); PG8_BAR; PG8_WAIT_L(0); PG8_MMA(0, 0, At, B0); PG8_BAR; PG8_SCHED;
;             PG8_LDB(B1, 1, 1); PG8_STAGE(PG8_SB(1, 0), b3, voffB);
;             PG8_BAR; PG8_WAIT_L(0); PG8_MMA(0, 1, At, B1); PG8_BAR;
	v_mfma_f32_16x16x32_bf16 v[2:5], v[238:241], v[222:225], v[2:5]
	s_setprio 0
	s_add_i32 s51, 0, 0x18000
	v_add_u32_e32 v163, s51, v144
	s_add_u32 s24, s76, 0x100000
	s_addc_u32 s25, s77, 0
	s_mov_b32 m0, s93
	v_lshl_add_u64 v[226:227], s[24:25], 0, v[136:137]
	ds_read_b128 v[218:221], v162 offset:38912
	ds_read_b128 v[222:225], v162 offset:39936
	global_load_lds_dwordx4 v[226:227], off
	v_lshl_add_u64 v[250:251], s[24:25], 0, v[132:133]
	s_mov_b32 m0, s94
	s_nop 0
	global_load_lds_dwordx4 v[250:251], off
	s_waitcnt lgkmcnt(8)
	s_barrier
	s_waitcnt lgkmcnt(0)
	s_setprio 1
	s_waitcnt lgkmcnt(0)
	v_mfma_f32_16x16x32_bf16 v[126:129], v[164:167], v[194:197], v[126:129]
	v_mfma_f32_16x16x32_bf16 v[126:129], v[182:185], v[198:201], v[126:129]
	v_mfma_f32_16x16x32_bf16 v[122:125], v[186:189], v[194:197], v[122:125]
	v_mfma_f32_16x16x32_bf16 v[122:125], v[190:193], v[198:201], v[122:125]
	v_mfma_f32_16x16x32_bf16 v[118:121], v[164:167], v[202:205], v[118:121]
	v_mfma_f32_16x16x32_bf16 v[118:121], v[182:185], v[206:209], v[118:121]
	v_mfma_f32_16x16x32_bf16 v[110:113], v[186:189], v[202:205], v[110:113]
	v_mfma_f32_16x16x32_bf16 v[110:113], v[190:193], v[206:209], v[110:113]
	v_mfma_f32_16x16x32_bf16 v[102:105], v[164:167], v[210:213], v[102:105]
	v_mfma_f32_16x16x32_bf16 v[102:105], v[182:185], v[214:217], v[102:105]
	v_mfma_f32_16x16x32_bf16 v[94:97], v[186:189], v[210:213], v[94:97]
	v_mfma_f32_16x16x32_bf16 v[94:97], v[190:193], v[214:217], v[94:97]
	v_mfma_f32_16x16x32_bf16 v[86:89], v[164:167], v[218:221], v[86:89]
	v_mfma_f32_16x16x32_bf16 v[86:89], v[182:185], v[222:225], v[86:89]
	v_mfma_f32_16x16x32_bf16 v[78:81], v[186:189], v[218:221], v[78:81]
	s_barrier
	v_mfma_f32_16x16x32_bf16 v[78:81], v[190:193], v[222:225], v[78:81]
	s_setprio 0
	s_add_i32 s76, 0, 0x1c000
	s_add_i32 s24, s51, s83
	v_add_u32_e32 v163, s76, v144
	v_lshl_add_u64 v[142:143], v[142:143], 0, s[12:13]
	s_mov_b32 m0, s24
	ds_read_b128 v[226:229], v163
	ds_read_b128 v[230:233], v163 offset:1024
	ds_read_b128 v[234:237], v163 offset:2048
	ds_read_b128 v[238:241], v163 offset:3072
	global_load_lds_dwordx4 v[142:143], off
	v_lshl_add_u64 v[250:251], v[168:169], 0, s[12:13]
	s_add_i32 m0, s24, 0x2000
	s_nop 0
	global_load_lds_dwordx4 v[250:251], off
	s_barrier
	s_waitcnt lgkmcnt(0)
	s_setprio 1
	s_waitcnt lgkmcnt(0)
	v_mfma_f32_16x16x32_bf16 v[114:117], v[226:229], v[194:197], v[114:117]
	v_mfma_f32_16x16x32_bf16 v[114:117], v[230:233], v[198:201], v[114:117]
	v_mfma_f32_16x16x32_bf16 v[106:109], v[234:237], v[194:197], v[106:109]
	v_mfma_f32_16x16x32_bf16 v[106:109], v[238:241], v[198:201], v[106:109]
	v_mfma_f32_16x16x32_bf16 v[98:101], v[226:229], v[202:205], v[98:101]
	v_mfma_f32_16x16x32_bf16 v[98:101], v[230:233], v[206:209], v[98:101]
	v_mfma_f32_16x16x32_bf16 v[90:93], v[234:237], v[202:205], v[90:93]
	v_mfma_f32_16x16x32_bf16 v[90:93], v[238:241], v[206:209], v[90:93]
	v_mfma_f32_16x16x32_bf16 v[82:85], v[226:229], v[210:213], v[82:85]
	v_mfma_f32_16x16x32_bf16 v[82:85], v[230:233], v[214:217], v[82:85]
	v_mfma_f32_16x16x32_bf16 v[74:77], v[234:237], v[210:213], v[74:77]
	v_mfma_f32_16x16x32_bf16 v[74:77], v[238:241], v[214:217], v[74:77]
	v_mfma_f32_16x16x32_bf16 v[70:73], v[226:229], v[218:221], v[70:73]
	v_mfma_f32_16x16x32_bf16 v[70:73], v[230:233], v[222:225], v[70:73]
	v_mfma_f32_16x16x32_bf16 v[66:69], v[234:237], v[218:221], v[66:69]
	s_barrier
; #define PG8_STAGE(bufoff, gbase, voff) do { _Pragma("unroll") for (int _i = 0; _i < 2; ++_i) \
;         __builtin_amdgcn_global_load_lds((const unsigned*)((const char*)(gbase) + (voff)[_i]), (LAS unsigned*)(lds + (bufoff) + ldsw + _i * 8192), 16, 0, 0); } while (0)
; #define PG8_LDA(dst, b, h) do { _Pragma("unroll") for (int m = 0; m < 4; ++m) _Pragma("unroll") for (int k = 0; k < 2; ++k) dst[m][k] = *(const LAS bf16x8*)(lds + PG8_SA(b, h) + aoff + m * 2048 + k * 1024); } while (0)
; #define PG8_MMA(ai, bj, At, Bt) do { __builtin_amdgcn_s_setprio(1); _Pragma("unroll") for (int m = 0; m < 4; ++m) _Pragma("unroll") for (int n = 0; n < 2; ++n) _Pragma("unroll") for (int k = 0; k < 2; ++k) \
;         acc[ai][bj][m][n] = __builtin_amdgcn_mfma_f32_16x16x32_bf16(Bt[n][k], At[m][k], acc[ai][bj][m][n], 0, 0, 0); __builtin_amdgcn_s_setprio(0); } while (0)
; #define PG8_WAIT_V(n) asm volatile("s_waitcnt vmcnt(" #n ")" ::: "memory")
; #define PG8_WAIT_L(n) asm volatile("s_waitcnt lgkmcnt(" #n ")" ::: "memory")
; #define PG8_BAR __builtin_amdgcn_s_barrier()
; #define PG8_SCHED __builtin_amdgcn_sched_barrier(0)
; template <class Epi, class Sched>
; __device__ __forceinline__ void gemm_phase(LAS unsigned char* lds, const Gemm g, const Sched& S, const Epi& E) {
;     ...
;             PG8_LDA(At, 1, 1); PG8_STAGE(PG8_SA(1, 0), a3, voffA);
;             PG8_BAR; PG8_WAIT_L(0); PG8_MMA(1, 0, At, B0); PG8_BAR; PG8_SCHED;
;             PG8_STAGE(PG8_SB(1, 1), b3 + hstep, voffB);
;             PG8_WAIT_V(6); PG8_BAR; PG8_MMA(1, 1, At, B1); PG8_BAR;
;         }
;         if (wr == 0) PG8_BAR;
	v_mfma_f32_16x16x32_bf16 v[66:69], v[238:241], v[222:225], v[66:69]
	s_setprio 0
	s_mov_b32 m0, s95
	v_lshl_add_u64 v[142:143], v[242:243], 0, s[12:13]
	ds_read_b128 v[194:197], v162 offset:49152
	ds_read_b128 v[198:201], v162 offset:50176
	ds_read_b128 v[202:205], v162 offset:51200
	ds_read_b128 v[206:209], v162 offset:52224
	ds_read_b128 v[210:213], v162 offset:53248
	ds_read_b128 v[214:217], v162 offset:54272
	ds_read_b128 v[218:221], v162 offset:55296
	ds_read_b128 v[222:225], v162 offset:56320
	global_load_lds_dwordx4 v[142:143], off
	v_lshl_add_u64 v[250:251], v[244:245], 0, s[12:13]
	s_mov_b32 m0, s96
	s_nop 0
	global_load_lds_dwordx4 v[250:251], off
	s_waitcnt vmcnt(8)
	s_barrier
	s_waitcnt lgkmcnt(0)
	s_setprio 1
	s_waitcnt lgkmcnt(0)
	v_mfma_f32_16x16x32_bf16 v[62:65], v[164:167], v[194:197], v[62:65]
	v_mfma_f32_16x16x32_bf16 v[62:65], v[182:185], v[198:201], v[62:65]
	v_mfma_f32_16x16x32_bf16 v[58:61], v[186:189], v[194:197], v[58:61]
	v_mfma_f32_16x16x32_bf16 v[58:61], v[190:193], v[198:201], v[58:61]
	v_mfma_f32_16x16x32_bf16 v[54:57], v[164:167], v[202:205], v[54:57]
	v_mfma_f32_16x16x32_bf16 v[54:57], v[182:185], v[206:209], v[54:57]
	v_mfma_f32_16x16x32_bf16 v[46:49], v[186:189], v[202:205], v[46:49]
	v_mfma_f32_16x16x32_bf16 v[46:49], v[190:193], v[206:209], v[46:49]
	v_mfma_f32_16x16x32_bf16 v[38:41], v[164:167], v[210:213], v[38:41]
	v_mfma_f32_16x16x32_bf16 v[38:41], v[182:185], v[214:217], v[38:41]
	v_mfma_f32_16x16x32_bf16 v[30:33], v[186:189], v[210:213], v[30:33]
	v_mfma_f32_16x16x32_bf16 v[30:33], v[190:193], v[214:217], v[30:33]
	v_mfma_f32_16x16x32_bf16 v[22:25], v[164:167], v[218:221], v[22:25]
	v_mfma_f32_16x16x32_bf16 v[22:25], v[182:185], v[222:225], v[22:25]
	v_mfma_f32_16x16x32_bf16 v[14:17], v[186:189], v[218:221], v[14:17]
	s_barrier
	v_mfma_f32_16x16x32_bf16 v[14:17], v[190:193], v[222:225], v[14:17]
	s_setprio 0
	s_add_u32 s24, s48, 0x100080
	s_addc_u32 s25, s49, 0
	s_add_i32 s48, s76, s83
	v_lshl_add_u64 v[142:143], s[24:25], 0, v[134:135]
	s_mov_b32 m0, s48
	s_nop 0
	global_load_lds_dwordx4 v[142:143], off
	v_lshl_add_u64 v[250:251], s[24:25], 0, v[130:131]
	s_add_i32 m0, s48, 0x2000
	s_nop 0
	global_load_lds_dwordx4 v[250:251], off
	s_waitcnt vmcnt(6)
	s_barrier
	s_setprio 1
	v_add_u32_e32 v249, 0x10000, v144
	v_mfma_f32_16x16x32_bf16 v[50:53], v[226:229], v[194:197], v[50:53]
	ds_read_b128 v[164:167], v249
	ds_read_b128 v[182:185], v249 offset:1024
	v_mfma_f32_16x16x32_bf16 v[50:53], v[230:233], v[198:201], v[50:53]
	ds_read_b128 v[186:189], v249 offset:2048
	ds_read_b128 v[190:193], v249 offset:3072
	v_mfma_f32_16x16x32_bf16 v[42:45], v[234:237], v[194:197], v[42:45]
	ds_read_b128 v[194:197], v162
	v_mfma_f32_16x16x32_bf16 v[42:45], v[238:241], v[198:201], v[42:45]
	ds_read_b128 v[198:201], v162 offset:1024
	v_mfma_f32_16x16x32_bf16 v[34:37], v[226:229], v[202:205], v[34:37]
	v_mfma_f32_16x16x32_bf16 v[34:37], v[230:233], v[206:209], v[34:37]
	v_mfma_f32_16x16x32_bf16 v[26:29], v[234:237], v[202:205], v[26:29]
	ds_read_b128 v[202:205], v162 offset:2048
	v_mfma_f32_16x16x32_bf16 v[26:29], v[238:241], v[206:209], v[26:29]
	ds_read_b128 v[206:209], v162 offset:3072
	v_mfma_f32_16x16x32_bf16 v[18:21], v[226:229], v[210:213], v[18:21]
	v_mfma_f32_16x16x32_bf16 v[18:21], v[230:233], v[214:217], v[18:21]
	v_mfma_f32_16x16x32_bf16 v[10:13], v[234:237], v[210:213], v[10:13]
	ds_read_b128 v[210:213], v162 offset:4096
	v_mfma_f32_16x16x32_bf16 v[10:13], v[238:241], v[214:217], v[10:13]
	ds_read_b128 v[214:217], v162 offset:5120
	v_mfma_f32_16x16x32_bf16 v[6:9], v[226:229], v[218:221], v[6:9]
	v_mfma_f32_16x16x32_bf16 v[6:9], v[230:233], v[222:225], v[6:9]
	v_mfma_f32_16x16x32_bf16 v[2:5], v[234:237], v[218:221], v[2:5]
	s_barrier
	v_mfma_f32_16x16x32_bf16 v[2:5], v[238:241], v[222:225], v[2:5]
	s_setprio 0
	s_add_i32 s98, s98, 2
	s_add_u32 s35, s35, 0x100
	s_addc_u32 s50, s50, 0
	s_add_u32 s0, s0, 0x100
	s_addc_u32 s1, s1, 0
	s_cmp_gt_u32 s98, 61
	s_cbranch_scc0 .LBB0_627
	s_waitcnt lgkmcnt(0)
	s_and_b64 vcc, exec, s[40:41]
	s_cbranch_vccz .LBB0_630
	s_barrier
